# LN phases: ds_bpermute butterflies replaced by DPP row reductions + readlane cross-row
# baseline (speedup 1.0000x reference)
; __device__ __forceinline__ void ln_panel(const float* src, float* dst, bf16_t* dstb, const float* gam, const float* bet, LAS f32x2* T) {
;     ...
;     for (int it = 0; it < 32 / NB; ++it) {
;         const int r = r0 + it * NB;
;         if (it + 1 < 32 / NB) {
; #pragma unroll
;             for (int b = 0; b < NB; ++b)
; #pragma unroll
;                 for (int j = 0; j < 4; ++j) nxt[b][j] = ((const f32x4*)(src + (size_t)(r + NB + b) * DM))[lane + 64 * j];
;         }
;         float s[NB], s2[NB];
; #pragma unroll
;         for (int b = 0; b < NB; ++b) { s[b] = 0.f;
; #pragma unroll
;             for (int j = 0; j < 4; ++j) s[b] += (cur[b][j].x + cur[b][j].y) + (cur[b][j].z + cur[b][j].w); }
; #pragma unroll
;         for (int o = 1; o < 64; o <<= 1)
; #pragma unroll
;             for (int b = 0; b < NB; ++b) s[b] += __shfl_xor(s[b], o);
; #pragma unroll
;         for (int b = 0; b < NB; ++b) { const float mean = s[b] * (1.f / DM); s2[b] = 0.f;
; #pragma unroll
;             for (int j = 0; j < 4; ++j) { cur[b][j] = cur[b][j] - mean; s2[b] += (cur[b][j].x * cur[b][j].x + cur[b][j].y * cur[b][j].y) + (cur[b][j].z * cur[b][j].z + cur[b][j].w * cur[b][j].w); } }
.LBB0_107:
	v_lshl_add_u64 v[66:67], v[102:103], 0, s[12:13]
	s_waitcnt vmcnt(15)
	v_mov_b32_e32 v68, v35
	v_mov_b32_e32 v69, v36
	v_mov_b32_e32 v70, v34
	v_mov_b32_e32 v71, v37
	s_waitcnt vmcnt(14)
	v_mov_b32_e32 v72, v39
	v_mov_b32_e32 v73, v40
	v_mov_b32_e32 v74, v38
	v_mov_b32_e32 v75, v41
	v_add_co_u32_e32 v110, vcc, 0x2000, v66
	s_waitcnt vmcnt(11)
	v_mov_b32_e32 v80, v51
	v_mov_b32_e32 v81, v52
	v_mov_b32_e32 v82, v50
	v_mov_b32_e32 v83, v53
	s_waitcnt vmcnt(10)
	v_mov_b32_e32 v84, v55
	v_mov_b32_e32 v85, v56
	v_mov_b32_e32 v86, v54
	v_mov_b32_e32 v87, v57
	v_pk_add_f32 v[68:69], v[68:69], v[70:71]
	v_pk_add_f32 v[70:71], v[72:73], v[74:75]
	v_addc_co_u32_e32 v111, vcc, 0, v67, vcc
	v_pk_add_f32 v[72:73], v[80:81], v[82:83]
	v_pk_add_f32 v[74:75], v[84:85], v[86:87]
	v_add_co_u32_e32 v116, vcc, 0x3000, v66
	v_add_f32_e32 v66, v68, v69
	v_pk_add_f32 v[118:119], v[70:71], v[70:71] op_sel:[0,1] op_sel_hi:[1,0]
	v_add_f32_e32 v76, v42, v43
	v_add_f32_e32 v78, v44, v45
	v_mov_b32_e32 v105, v46
	v_mov_b32_e32 v77, v48
	v_mov_b32_e32 v79, v49
	v_add_f32_e32 v68, v72, v73
	v_pk_add_f32 v[120:121], v[74:75], v[74:75] op_sel:[0,1] op_sel_hi:[1,0]
	v_add_f32_e32 v104, 0, v66
	v_mov_b32_e32 v119, v47
	s_waitcnt vmcnt(9)
	v_add_f32_e32 v88, v58, v59
	v_add_f32_e32 v90, v60, v61
	s_waitcnt vmcnt(8)
	v_mov_b32_e32 v107, v62
	v_mov_b32_e32 v89, v64
	v_mov_b32_e32 v91, v65
	v_pk_add_f32 v[112:113], v[76:77], v[78:79]
	v_add_f32_e32 v106, 0, v68
	v_mov_b32_e32 v121, v63
	v_pk_add_f32 v[104:105], v[104:105], v[118:119]
	v_pk_add_f32 v[114:115], v[88:89], v[90:91]
	v_pk_add_f32 v[106:107], v[106:107], v[120:121]
	v_pk_add_f32 v[104:105], v[104:105], v[112:113]
	v_pk_add_f32 v[106:107], v[106:107], v[114:115]
	v_add_f32_e32 v104, v104, v105
	v_add_f32_e32 v105, v106, v107
	v_addc_co_u32_e32 v117, vcc, 0, v67, vcc
	global_load_dwordx4 v[94:97], v[110:111], off
	global_load_dwordx4 v[90:93], v[110:111], off offset:1024
	global_load_dwordx4 v[86:89], v[110:111], off offset:2048
	global_load_dwordx4 v[82:85], v[110:111], off offset:3072
	s_waitcnt lgkmcnt(1)
	s_nop 1
	v_add_f32_dpp v104, v104, v104 quad_perm:[1,0,3,2] row_mask:0xf bank_mask:0xf
	s_waitcnt lgkmcnt(0)
	s_nop 1
	v_add_f32_dpp v105, v105, v105 quad_perm:[1,0,3,2] row_mask:0xf bank_mask:0xf
	global_load_dwordx4 v[78:81], v[116:117], off
	global_load_dwordx4 v[74:77], v[116:117], off offset:1024
	global_load_dwordx4 v[70:73], v[116:117], off offset:2048
	global_load_dwordx4 v[66:69], v[116:117], off offset:3072
	s_add_u32 s12, s12, 0x2000
	s_addc_u32 s13, s13, 0
	s_waitcnt lgkmcnt(1)
	s_nop 1
	v_add_f32_dpp v104, v104, v104 quad_perm:[2,3,0,1] row_mask:0xf bank_mask:0xf
	s_waitcnt lgkmcnt(0)
	s_nop 1
	v_add_f32_dpp v105, v105, v105 quad_perm:[2,3,0,1] row_mask:0xf bank_mask:0xf
	s_cmp_eq_u32 s12, 0x1e000
	s_waitcnt lgkmcnt(1)
	s_nop 1
	v_add_f32_dpp v104, v104, v104 row_half_mirror row_mask:0xf bank_mask:0xf
	s_waitcnt lgkmcnt(0)
	s_nop 1
	v_add_f32_dpp v105, v105, v105 row_half_mirror row_mask:0xf bank_mask:0xf
	s_waitcnt lgkmcnt(1)
	s_nop 1
	v_add_f32_dpp v104, v104, v104 row_mirror row_mask:0xf bank_mask:0xf
	s_waitcnt lgkmcnt(0)
	s_nop 1
	v_add_f32_dpp v105, v105, v105 row_mirror row_mask:0xf bank_mask:0xf
	s_waitcnt lgkmcnt(1)
	s_waitcnt lgkmcnt(0)
	s_waitcnt lgkmcnt(1)
	s_nop 0
	v_readlane_b32 s98, v104, 0
	v_readlane_b32 s99, v104, 16
	v_readlane_b32 s100, v104, 32
	v_readlane_b32 s101, v104, 48
	v_mov_b32_e32 v104, s98
	v_add_f32_e32 v104, s99, v104
	v_mov_b32_e32 v106, s100
	v_add_f32_e32 v106, s101, v106
	v_add_f32_e32 v104, v104, v106
	s_waitcnt lgkmcnt(0)
	s_nop 0
	v_readlane_b32 s98, v105, 0
	v_readlane_b32 s99, v105, 16
	v_readlane_b32 s100, v105, 32
	v_readlane_b32 s101, v105, 48
	v_mov_b32_e32 v105, s98
	v_add_f32_e32 v105, s99, v105
	v_mov_b32_e32 v107, s100
	v_add_f32_e32 v107, s101, v107
	v_add_f32_e32 v105, v105, v107
	v_fmamk_f32 v35, v104, 0xba800000, v35
	v_fmamk_f32 v34, v104, 0xba800000, v34
	v_fmamk_f32 v37, v104, 0xba800000, v37
	v_fmac_f32_e32 v36, 0xba800000, v104
	v_fmamk_f32 v39, v104, 0xba800000, v39
	v_fmamk_f32 v38, v104, 0xba800000, v38
	v_fmamk_f32 v41, v104, 0xba800000, v41
	v_fmac_f32_e32 v40, 0xba800000, v104
	v_fmamk_f32 v43, v104, 0xba800000, v43
	v_fmamk_f32 v42, v104, 0xba800000, v42
	v_fmamk_f32 v45, v104, 0xba800000, v45
	v_fmac_f32_e32 v44, 0xba800000, v104
	v_fmamk_f32 v49, v104, 0xba800000, v49
	v_fmamk_f32 v48, v104, 0xba800000, v48
	v_fmamk_f32 v47, v104, 0xba800000, v47
	v_fmac_f32_e32 v46, 0xba800000, v104
	v_fmamk_f32 v51, v105, 0xba800000, v51
	v_fmamk_f32 v50, v105, 0xba800000, v50
	v_fmamk_f32 v53, v105, 0xba800000, v53
	v_fmac_f32_e32 v52, 0xba800000, v105
	v_fmamk_f32 v55, v105, 0xba800000, v55
	v_fmamk_f32 v54, v105, 0xba800000, v54
	v_fmamk_f32 v57, v105, 0xba800000, v57
	v_fmac_f32_e32 v56, 0xba800000, v105
	v_fmamk_f32 v59, v105, 0xba800000, v59
	v_fmamk_f32 v58, v105, 0xba800000, v58
	v_fmamk_f32 v61, v105, 0xba800000, v61
	v_fmac_f32_e32 v60, 0xba800000, v105
	v_fmamk_f32 v65, v105, 0xba800000, v65
	v_fmamk_f32 v64, v105, 0xba800000, v64
	v_fmamk_f32 v63, v105, 0xba800000, v63
	v_fmac_f32_e32 v62, 0xba800000, v105
	v_pk_mul_f32 v[104:105], v[36:37], v[36:37]
	v_pk_mul_f32 v[106:107], v[34:35], v[34:35]
	v_pk_mul_f32 v[110:111], v[40:41], v[40:41]
	v_pk_mul_f32 v[112:113], v[38:39], v[38:39]
	v_mul_f32_e32 v114, v42, v42
	v_mul_f32_e32 v116, v44, v44
	v_pk_mul_f32 v[118:119], v[52:53], v[52:53]
	v_pk_mul_f32 v[120:121], v[50:51], v[50:51]
	v_pk_mul_f32 v[122:123], v[56:57], v[56:57]
	v_pk_mul_f32 v[124:125], v[54:55], v[54:55]
	v_pk_mov_b32 v[130:131], v[106:107], v[104:105] op_sel:[1,0]
	v_mov_b32_e32 v107, v105
; __device__ __forceinline__ void ln_panel(const float* src, float* dst, bf16_t* dstb, const float* gam, const float* bet, LAS f32x2* T) {
;     ...
; #pragma unroll
;         for (int o = 1; o < 64; o <<= 1)
; #pragma unroll
;             for (int b = 0; b < NB; ++b) s2[b] += __shfl_xor(s2[b], o);
; #pragma unroll
;         for (int b = 0; b < NB; ++b) {
;             const float rstd = 1.f / sqrtf(s2[b] * (1.f / DM) + LN_EPS);
;             if (T && lane == 0) T[r + b] = (f32x2){s[b] * (1.f / DM), rstd};
; #pragma unroll
;             for (int j = 0; j < 4; ++j) {
;                 const f32x4 o = cur[b][j] * rstd * gv[j] + bv[j];
	v_pk_mov_b32 v[104:105], v[112:113], v[110:111] op_sel:[1,0]
	v_mov_b32_e32 v113, v111
	v_pk_fma_f32 v[110:111], v[42:43], v[42:43], v[114:115] op_sel_hi:[1,1,0]
	v_pk_fma_f32 v[114:115], v[44:45], v[44:45], v[116:117] op_sel_hi:[1,1,0]
	v_pk_mov_b32 v[116:117], v[120:121], v[118:119] op_sel:[1,0]
	v_mov_b32_e32 v121, v119
	v_pk_mov_b32 v[118:119], v[124:125], v[122:123] op_sel:[1,0]
	v_mov_b32_e32 v125, v123
	v_pk_add_f32 v[106:107], v[130:131], v[106:107]
	v_pk_add_f32 v[104:105], v[104:105], v[112:113]
	v_mul_f32_e32 v126, v58, v58
	v_mul_f32_e32 v128, v60, v60
	v_mul_f32_e32 v110, v46, v46
	v_mul_f32_e32 v114, v47, v47
	v_pk_add_f32 v[112:113], v[116:117], v[120:121]
	v_pk_add_f32 v[116:117], v[118:119], v[124:125]
	v_pk_add_f32 v[106:107], v[106:107], v[106:107] op_sel_hi:[0,1]
	v_pk_add_f32 v[104:105], v[104:105], v[104:105] op_sel_hi:[0,1]
	v_pk_fma_f32 v[122:123], v[58:59], v[58:59], v[126:127] op_sel_hi:[1,1,0]
	v_pk_fma_f32 v[126:127], v[60:61], v[60:61], v[128:129] op_sel_hi:[1,1,0]
	v_pk_add_f32 v[110:111], v[110:111], v[114:115]
	v_pk_add_f32 v[112:113], v[112:113], v[112:113] op_sel_hi:[0,1]
	v_pk_add_f32 v[114:115], v[116:117], v[116:117] op_sel_hi:[0,1]
	v_mul_f32_e32 v106, v48, v48
	v_mul_f32_e32 v104, v49, v49
	v_mul_f32_e32 v122, v62, v62
	v_mul_f32_e32 v126, v63, v63
	v_mul_f32_e32 v112, v64, v64
	v_mul_f32_e32 v114, v65, v65
	v_pk_add_f32 v[104:105], v[106:107], v[104:105]
	v_pk_add_f32 v[116:117], v[122:123], v[126:127]
	v_pk_add_f32 v[106:107], v[112:113], v[114:115]
	v_pk_add_f32 v[104:105], v[110:111], v[104:105]
	v_pk_add_f32 v[106:107], v[116:117], v[106:107]
	v_add_f32_e32 v104, v104, v105
	v_add_f32_e32 v105, v106, v107
	s_waitcnt lgkmcnt(1)
	s_nop 1
	v_add_f32_dpp v104, v104, v104 quad_perm:[1,0,3,2] row_mask:0xf bank_mask:0xf
	s_waitcnt lgkmcnt(0)
	s_nop 1
	v_add_f32_dpp v105, v105, v105 quad_perm:[1,0,3,2] row_mask:0xf bank_mask:0xf
	s_waitcnt lgkmcnt(1)
	s_nop 1
	v_add_f32_dpp v104, v104, v104 quad_perm:[2,3,0,1] row_mask:0xf bank_mask:0xf
	s_waitcnt lgkmcnt(0)
	s_nop 1
	v_add_f32_dpp v105, v105, v105 quad_perm:[2,3,0,1] row_mask:0xf bank_mask:0xf
	s_waitcnt lgkmcnt(1)
	s_nop 1
	v_add_f32_dpp v104, v104, v104 row_half_mirror row_mask:0xf bank_mask:0xf
	s_waitcnt lgkmcnt(0)
	s_nop 1
	v_add_f32_dpp v105, v105, v105 row_half_mirror row_mask:0xf bank_mask:0xf
	s_waitcnt lgkmcnt(1)
	s_nop 1
	v_add_f32_dpp v104, v104, v104 row_mirror row_mask:0xf bank_mask:0xf
	s_waitcnt lgkmcnt(0)
	s_nop 1
	v_add_f32_dpp v105, v105, v105 row_mirror row_mask:0xf bank_mask:0xf
	s_waitcnt lgkmcnt(1)
	s_waitcnt lgkmcnt(0)
	s_waitcnt lgkmcnt(1)
	s_nop 0
	v_readlane_b32 s98, v104, 0
	v_readlane_b32 s99, v104, 16
	v_readlane_b32 s100, v104, 32
	v_readlane_b32 s101, v104, 48
	v_mov_b32_e32 v104, s98
	v_add_f32_e32 v104, s99, v104
	v_mov_b32_e32 v106, s100
	v_add_f32_e32 v106, s101, v106
	v_add_f32_e32 v104, v104, v106
	s_waitcnt lgkmcnt(0)
	s_nop 0
	v_readlane_b32 s98, v105, 0
	v_readlane_b32 s99, v105, 16
	v_readlane_b32 s100, v105, 32
	v_readlane_b32 s101, v105, 48
	v_mov_b32_e32 v105, s98
	v_add_f32_e32 v105, s99, v105
	v_mov_b32_e32 v107, s100
	v_add_f32_e32 v107, s101, v107
	v_add_f32_e32 v105, v105, v107
	v_fmamk_f32 v104, v104, 0x3a800000, v99
	v_fmamk_f32 v105, v105, 0x3a800000, v99
	v_mul_f32_e32 v106, 0x4f800000, v104
	v_cmp_gt_f32_e64 s[4:5], s11, v104
	v_mul_f32_e32 v107, 0x4f800000, v105
	v_cmp_gt_f32_e32 vcc, s11, v105
	v_cndmask_b32_e64 v104, v104, v106, s[4:5]
	v_sqrt_f32_e32 v106, v104
	v_cndmask_b32_e32 v105, v105, v107, vcc
	v_sqrt_f32_e32 v107, v105
	v_add_u32_e32 v109, -1, v106
	v_add_u32_e32 v110, 1, v106
	v_add_u32_e32 v111, -1, v107
	v_fma_f32 v113, -v109, v106, v104
	v_add_u32_e32 v112, 1, v107
	v_fma_f32 v114, -v110, v106, v104
	v_fma_f32 v115, -v111, v107, v105
	v_cmp_ge_f32_e64 s[6:7], 0, v113
	v_fma_f32 v116, -v112, v107, v105
	v_cmp_lt_f32_e64 s[8:9], 0, v114
	v_cndmask_b32_e64 v106, v106, v109, s[6:7]
	v_cmp_ge_f32_e64 s[6:7], 0, v115
	v_cndmask_b32_e64 v106, v106, v110, s[8:9]
	v_mul_f32_e32 v109, 0x37800000, v106
	v_cndmask_b32_e64 v107, v107, v111, s[6:7]
	v_cmp_lt_f32_e64 s[6:7], 0, v116
	v_cndmask_b32_e64 v106, v106, v109, s[4:5]
	v_cmp_class_f32_e64 s[4:5], v104, v108
	v_cndmask_b32_e64 v107, v107, v112, s[6:7]
	v_mul_f32_e32 v110, 0x37800000, v107
	v_cndmask_b32_e32 v107, v107, v110, vcc
	v_cmp_class_f32_e32 vcc, v105, v108
	v_cndmask_b32_e64 v104, v106, v104, s[4:5]
	s_nop 0
	v_cndmask_b32_e32 v109, v107, v105, vcc
	v_div_scale_f32 v105, s[4:5], v104, v104, 1.0
	v_rcp_f32_e32 v111, v105
	v_div_scale_f32 v107, s[4:5], v109, v109, 1.0
	v_rcp_f32_e32 v112, v107
	v_fma_f32 v113, -v105, v111, 1.0
	v_div_scale_f32 v106, vcc, 1.0, v104, 1.0
	v_fmac_f32_e32 v111, v113, v111
	v_fma_f32 v114, -v107, v112, 1.0
	v_mul_f32_e32 v113, v106, v111
	v_div_scale_f32 v110, s[4:5], 1.0, v109, 1.0
	v_fmac_f32_e32 v112, v114, v112
	v_fma_f32 v115, -v105, v113, v106
	v_mul_f32_e32 v114, v110, v112
	v_fmac_f32_e32 v113, v115, v111
	v_fma_f32 v116, -v107, v114, v110
	v_fma_f32 v105, -v105, v113, v106
	v_fmac_f32_e32 v114, v116, v112
	v_div_fmas_f32 v105, v105, v111, v113
	v_fma_f32 v106, -v107, v114, v110
	v_div_fixup_f32 v104, v105, v104, 1.0
	s_mov_b64 vcc, s[4:5]
	v_div_fmas_f32 v122, v106, v112, v114
	v_pk_mul_f32 v[106:107], v[34:35], v[104:105] op_sel_hi:[1,0]
	v_pk_mul_f32 v[110:111], v[36:37], v[104:105] op_sel_hi:[1,0]
	v_pk_mul_f32 v[112:113], v[38:39], v[104:105] op_sel_hi:[1,0]
	v_pk_mul_f32 v[114:115], v[40:41], v[104:105] op_sel_hi:[1,0]
	v_pk_mul_f32 v[116:117], v[42:43], v[104:105] op_sel_hi:[1,0]
	v_pk_mul_f32 v[118:119], v[44:45], v[104:105] op_sel_hi:[1,0]
	v_pk_mul_f32 v[120:121], v[46:47], v[104:105] op_sel_hi:[1,0]
	v_pk_mul_f32 v[104:105], v[48:49], v[104:105] op_sel_hi:[1,0]
	v_div_fixup_f32 v122, v122, v109, 1.0
	s_waitcnt vmcnt(13)
; __device__ __forceinline__ unsigned pk2(float lo, float hi) { unsigned r; asm("v_cvt_pk_bf16_f32 %0, %1, %2" : "=v"(r) : "v"(lo), "v"(hi)); return r; }
; __device__ __forceinline__ void ln_panel(const float* src, float* dst, bf16_t* dstb, const float* gam, const float* bet, LAS f32x2* T) {
;     ...
;         float s[NB], s2[NB];
; #pragma unroll
;         for (int b = 0; b < NB; ++b) { s[b] = 0.f;
; #pragma unroll
;             for (int j = 0; j < 4; ++j) s[b] += (cur[b][j].x + cur[b][j].y) + (cur[b][j].z + cur[b][j].w); }
; #pragma unroll
;         for (int o = 1; o < 64; o <<= 1)
; #pragma unroll
;             for (int b = 0; b < NB; ++b) s[b] += __shfl_xor(s[b], o);
;     ...
; #pragma unroll
;             for (int j = 0; j < 4; ++j) {
;                 const f32x4 o = cur[b][j] * rstd * gv[j] + bv[j];
;                 if (dst) ((f32x4*)(dst + (size_t)(r + b) * DM))[lane + 64 * j] = o;
;                 if (dstb) { u32x2 w; w.x = pk2(o.x, o.y); w.y = pk2(o.z, o.w); ((u32x2*)(dstb + (size_t)(r + b) * DM))[lane + 64 * j] = w; }
;             }
;         }
; #pragma unroll
;         for (int b = 0; b < NB; ++b)
; #pragma unroll
;             for (int j = 0; j < 4; ++j) cur[b][j] = nxt[b][j];
	v_pk_fma_f32 v[106:107], v[26:27], v[106:107], v[30:31]
	v_pk_fma_f32 v[110:111], v[28:29], v[110:111], v[32:33]
	s_waitcnt vmcnt(12)
	v_pk_fma_f32 v[114:115], v[20:21], v[114:115], v[24:25]
	v_pk_fma_f32 v[112:113], v[18:19], v[112:113], v[22:23]
	s_waitcnt vmcnt(9)
	v_pk_fma_f32 v[116:117], v[10:11], v[116:117], v[14:15]
	s_waitcnt vmcnt(8)
	v_pk_fma_f32 v[104:105], v[4:5], v[104:105], v[8:9]
	v_pk_mul_f32 v[124:125], v[50:51], v[122:123] op_sel_hi:[1,0]
	v_pk_mul_f32 v[126:127], v[52:53], v[122:123] op_sel_hi:[1,0]
	v_cvt_pk_bf16_f32 v106, v106, v107
	v_cvt_pk_bf16_f32 v107, v110, v111
	s_waitcnt vmcnt(7)
	v_mov_b64_e32 v[34:35], v[94:95]
	s_waitcnt vmcnt(6)
	v_mov_b64_e32 v[38:39], v[90:91]
	s_waitcnt vmcnt(5)
	v_mov_b64_e32 v[42:43], v[86:87]
	s_waitcnt vmcnt(4)
	v_mov_b64_e32 v[46:47], v[82:83]
	v_pk_fma_f32 v[118:119], v[12:13], v[118:119], v[16:17]
	v_pk_fma_f32 v[120:121], v[2:3], v[120:121], v[6:7]
	v_pk_mul_f32 v[128:129], v[54:55], v[122:123] op_sel_hi:[1,0]
	v_pk_mul_f32 v[130:131], v[56:57], v[122:123] op_sel_hi:[1,0]
	v_pk_mul_f32 v[132:133], v[58:59], v[122:123] op_sel_hi:[1,0]
	v_pk_mul_f32 v[134:135], v[60:61], v[122:123] op_sel_hi:[1,0]
	v_pk_mul_f32 v[136:137], v[62:63], v[122:123] op_sel_hi:[1,0]
	v_pk_mul_f32 v[122:123], v[64:65], v[122:123] op_sel_hi:[1,0]
	s_waitcnt vmcnt(3)
	v_mov_b64_e32 v[50:51], v[78:79]
	s_waitcnt vmcnt(2)
	v_mov_b64_e32 v[54:55], v[74:75]
	s_waitcnt vmcnt(1)
	v_mov_b64_e32 v[58:59], v[70:71]
	s_waitcnt vmcnt(0)
	v_mov_b64_e32 v[62:63], v[66:67]
	v_cvt_pk_bf16_f32 v110, v112, v113
	v_cvt_pk_bf16_f32 v111, v114, v115
	v_cvt_pk_bf16_f32 v112, v116, v117
	v_cvt_pk_bf16_f32 v113, v118, v119
	v_cvt_pk_bf16_f32 v114, v120, v121
	v_cvt_pk_bf16_f32 v115, v104, v105
	v_pk_fma_f32 v[104:105], v[28:29], v[126:127], v[32:33]
	v_pk_fma_f32 v[116:117], v[26:27], v[124:125], v[30:31]
	global_store_dwordx2 v[100:101], v[106:107], off offset:-2048
	global_store_dwordx2 v[100:101], v[110:111], off offset:-1536
	global_store_dwordx2 v[100:101], v[112:113], off offset:-1024
	global_store_dwordx2 v[100:101], v[114:115], off offset:-512
	v_cvt_pk_bf16_f32 v106, v116, v117
	v_cvt_pk_bf16_f32 v107, v104, v105
	v_mov_b64_e32 v[36:37], v[96:97]
	v_mov_b64_e32 v[40:41], v[92:93]
	v_mov_b64_e32 v[44:45], v[88:89]
	v_mov_b64_e32 v[48:49], v[84:85]
	v_mov_b64_e32 v[52:53], v[80:81]
	v_mov_b64_e32 v[56:57], v[76:77]
	v_mov_b64_e32 v[60:61], v[72:73]
	v_mov_b64_e32 v[64:65], v[68:69]
	v_pk_fma_f32 v[118:119], v[20:21], v[130:131], v[24:25]
	v_pk_fma_f32 v[120:121], v[18:19], v[128:129], v[22:23]
	v_pk_fma_f32 v[124:125], v[12:13], v[134:135], v[16:17]
	v_pk_fma_f32 v[126:127], v[10:11], v[132:133], v[14:15]
	v_pk_fma_f32 v[122:123], v[4:5], v[122:123], v[8:9]
	v_pk_fma_f32 v[128:129], v[2:3], v[136:137], v[6:7]
	v_cvt_pk_bf16_f32 v104, v120, v121
	v_cvt_pk_bf16_f32 v105, v118, v119
	v_cvt_pk_bf16_f32 v110, v126, v127
	v_cvt_pk_bf16_f32 v111, v124, v125
	v_cvt_pk_bf16_f32 v113, v122, v123
	s_nop 0
	v_cvt_pk_bf16_f32 v112, v128, v129
	global_store_dwordx2 v[100:101], v[106:107], off
	global_store_dwordx2 v[100:101], v[104:105], off offset:512
	global_store_dwordx2 v[100:101], v[110:111], off offset:1024
	global_store_dwordx2 v[100:101], v[112:113], off offset:1536
	v_lshl_add_u64 v[100:101], v[100:101], 0, s[14:15]
	s_cbranch_scc0 .LBB0_107
	v_mov_b32_e32 v34, v95
	v_mov_b32_e32 v35, v96
	v_mov_b32_e32 v36, v94
	v_mov_b32_e32 v37, v97
	v_pk_add_f32 v[34:35], v[34:35], v[36:37]
	v_mov_b32_e32 v36, v91
	v_mov_b32_e32 v37, v92
	v_mov_b32_e32 v38, v90
	v_mov_b32_e32 v39, v93
	v_pk_add_f32 v[36:37], v[36:37], v[38:39]
	v_add_f32_e32 v34, v34, v35
	v_pk_add_f32 v[36:37], v[36:37], v[36:37] op_sel:[0,1] op_sel_hi:[1,0]
	v_add_f32_e32 v34, 0, v34
	v_add_f32_e32 v38, v86, v87
	v_add_f32_e32 v40, v88, v89
	v_mov_b32_e32 v35, v82
	v_mov_b32_e32 v37, v83
	v_mov_b32_e32 v39, v84
	v_mov_b32_e32 v41, v85
	v_pk_add_f32 v[34:35], v[34:35], v[36:37]
	v_pk_add_f32 v[36:37], v[38:39], v[40:41]
	v_mov_b32_e32 v38, v74
	v_pk_add_f32 v[34:35], v[34:35], v[36:37]
	v_mov_b32_e32 v36, v78
	v_add_f32_e32 v42, v34, v35
	v_mov_b32_e32 v34, v79
	v_mov_b32_e32 v35, v80
	v_mov_b32_e32 v37, v81
	v_pk_add_f32 v[34:35], v[34:35], v[36:37]
	v_mov_b32_e32 v36, v75
	v_mov_b32_e32 v37, v76
	v_mov_b32_e32 v39, v77
	v_pk_add_f32 v[36:37], v[36:37], v[38:39]
	v_add_f32_e32 v34, v34, v35
	v_pk_add_f32 v[36:37], v[36:37], v[36:37] op_sel:[0,1] op_sel_hi:[1,0]
	v_add_f32_e32 v34, 0, v34
	v_add_f32_e32 v38, v70, v71
	v_add_f32_e32 v40, v72, v73
	v_mov_b32_e32 v35, v66
	v_mov_b32_e32 v37, v67
	v_mov_b32_e32 v39, v68
	v_mov_b32_e32 v41, v69
	v_pk_add_f32 v[34:35], v[34:35], v[36:37]
	v_pk_add_f32 v[36:37], v[38:39], v[40:41]
	s_mov_b32 s11, 0xf800000
	v_pk_add_f32 v[34:35], v[34:35], v[36:37]
	v_readlane_b32 s4, v249, 4
	v_add_f32_e32 v34, v34, v35
	v_readlane_b32 s5, v249, 5
	s_lshl_b64 s[6:7], s[4:5], 1
	s_add_u32 s4, s24, s6
	s_waitcnt lgkmcnt(1)
	s_nop 1
	v_add_f32_dpp v35, v42, v42 quad_perm:[1,0,3,2] row_mask:0xf bank_mask:0xf
	s_waitcnt lgkmcnt(0)
	s_nop 1
	v_add_f32_dpp v34, v34, v34 quad_perm:[1,0,3,2] row_mask:0xf bank_mask:0xf
	v_writelane_b32 v249, s6, 8
	s_addc_u32 s5, s25, s7
	s_add_u32 s8, s4, 0x6000000
	s_waitcnt lgkmcnt(1)
	s_nop 1
	v_add_f32_dpp v35, v35, v35 quad_perm:[2,3,0,1] row_mask:0xf bank_mask:0xf
	s_waitcnt lgkmcnt(1)
	s_nop 1
	v_add_f32_dpp v34, v34, v34 quad_perm:[2,3,0,1] row_mask:0xf bank_mask:0xf
	s_addc_u32 s9, s5, 0
	v_writelane_b32 v249, s7, 9
	s_waitcnt lgkmcnt(1)
	s_nop 1
	v_add_f32_dpp v35, v35, v35 row_half_mirror row_mask:0xf bank_mask:0xf
	s_waitcnt lgkmcnt(1)
; __device__ __forceinline__ void ln_panel(const float* src, float* dst, bf16_t* dstb, const float* gam, const float* bet, LAS f32x2* T) {
;     ...
;             for (int b = 0; b < NB; ++b) s[b] += __shfl_xor(s[b], o);
; #pragma unroll
;         for (int b = 0; b < NB; ++b) { const float mean = s[b] * (1.f / DM); s2[b] = 0.f;
; #pragma unroll
;             for (int j = 0; j < 4; ++j) { cur[b][j] = cur[b][j] - mean; s2[b] += (cur[b][j].x * cur[b][j].x + cur[b][j].y * cur[b][j].y) + (cur[b][j].z * cur[b][j].z + cur[b][j].w * cur[b][j].w); } }
; #pragma unroll
;         for (int o = 1; o < 64; o <<= 1)
; #pragma unroll
;             for (int b = 0; b < NB; ++b) s2[b] += __shfl_xor(s2[b], o);
	s_nop 1
	v_add_f32_dpp v34, v34, v34 row_half_mirror row_mask:0xf bank_mask:0xf
	s_or_b32 s6, s10, 30
	s_ashr_i32 s7, s6, 31
	s_waitcnt lgkmcnt(1)
	s_nop 1
	v_add_f32_dpp v35, v35, v35 row_mirror row_mask:0xf bank_mask:0xf
	s_waitcnt lgkmcnt(1)
	s_nop 1
	v_add_f32_dpp v34, v34, v34 row_mirror row_mask:0xf bank_mask:0xf
	s_waitcnt lgkmcnt(1)
	s_waitcnt lgkmcnt(1)
	s_waitcnt lgkmcnt(1)
	s_nop 0
	v_readlane_b32 s98, v35, 0
	v_readlane_b32 s99, v35, 16
	v_readlane_b32 s100, v35, 32
	v_readlane_b32 s101, v35, 48
	v_mov_b32_e32 v50, s98
	v_add_f32_e32 v50, s99, v50
	v_mov_b32_e32 v36, s100
	v_add_f32_e32 v36, s101, v36
	v_add_f32_e32 v50, v50, v36
	v_fmamk_f32 v43, v50, 0xba800000, v95
	v_fmamk_f32 v42, v50, 0xba800000, v94
	v_fmamk_f32 v97, v50, 0xba800000, v97
	v_fmac_f32_e32 v96, 0xba800000, v50
	s_waitcnt lgkmcnt(0)
	s_nop 0
	v_readlane_b32 s98, v34, 0
	v_readlane_b32 s99, v34, 16
	v_readlane_b32 s100, v34, 32
	v_readlane_b32 s101, v34, 48
	v_mov_b32_e32 v58, s98
	v_add_f32_e32 v58, s99, v58
	v_mov_b32_e32 v37, s100
	v_add_f32_e32 v37, s101, v37
	v_add_f32_e32 v58, v58, v37
	v_pk_mul_f32 v[34:35], v[96:97], v[96:97]
	v_pk_mul_f32 v[36:37], v[42:43], v[42:43]
	v_fmamk_f32 v45, v50, 0xba800000, v91
	v_pk_mov_b32 v[38:39], v[36:37], v[34:35] op_sel:[1,0]
	v_mov_b32_e32 v37, v35
	v_pk_add_f32 v[34:35], v[38:39], v[36:37]
	v_fmamk_f32 v44, v50, 0xba800000, v90
	v_fmamk_f32 v93, v50, 0xba800000, v93
	v_fmac_f32_e32 v92, 0xba800000, v50
	v_pk_add_f32 v[34:35], v[34:35], v[34:35] op_sel_hi:[0,1]
	v_pk_mul_f32 v[36:37], v[92:93], v[92:93]
	v_pk_mul_f32 v[38:39], v[44:45], v[44:45]
	v_fmamk_f32 v46, v50, 0xba800000, v86
	v_pk_mov_b32 v[40:41], v[38:39], v[36:37] op_sel:[1,0]
	v_mov_b32_e32 v39, v37
	v_fmamk_f32 v47, v50, 0xba800000, v87
	v_fmac_f32_e32 v88, 0xba800000, v50
	v_mul_f32_e32 v34, v46, v46
	v_pk_add_f32 v[36:37], v[40:41], v[38:39]
	v_fmamk_f32 v89, v50, 0xba800000, v89
	v_pk_fma_f32 v[38:39], v[46:47], v[46:47], v[34:35] op_sel_hi:[1,1,0]
	v_mul_f32_e32 v34, v88, v88
	v_pk_add_f32 v[36:37], v[36:37], v[36:37] op_sel_hi:[0,1]
	v_pk_fma_f32 v[40:41], v[88:89], v[88:89], v[34:35] op_sel_hi:[1,1,0]
	v_fmamk_f32 v49, v50, 0xba800000, v85
	v_fmamk_f32 v48, v50, 0xba800000, v84
	v_fmamk_f32 v83, v50, 0xba800000, v83
	v_fmac_f32_e32 v82, 0xba800000, v50
	v_mul_f32_e32 v38, v82, v82
	v_mul_f32_e32 v40, v83, v83
	v_mul_f32_e32 v34, v48, v48
	v_mul_f32_e32 v36, v49, v49
	v_pk_add_f32 v[38:39], v[38:39], v[40:41]
	v_pk_add_f32 v[34:35], v[34:35], v[36:37]
	v_fmamk_f32 v81, v58, 0xba800000, v81
	v_pk_add_f32 v[34:35], v[38:39], v[34:35]
	v_fmac_f32_e32 v80, 0xba800000, v58
	v_add_f32_e32 v59, v34, v35
	v_fmamk_f32 v35, v58, 0xba800000, v79
	v_fmamk_f32 v34, v58, 0xba800000, v78
	v_pk_mul_f32 v[36:37], v[80:81], v[80:81]
	v_pk_mul_f32 v[38:39], v[34:35], v[34:35]
	v_fmamk_f32 v77, v58, 0xba800000, v77
	v_pk_mov_b32 v[40:41], v[38:39], v[36:37] op_sel:[1,0]
	v_mov_b32_e32 v39, v37
	v_pk_add_f32 v[36:37], v[40:41], v[38:39]
	v_fmamk_f32 v39, v58, 0xba800000, v75
	v_fmamk_f32 v38, v58, 0xba800000, v74
	v_fmac_f32_e32 v76, 0xba800000, v58
	v_pk_add_f32 v[50:51], v[36:37], v[36:37] op_sel_hi:[0,1]
	v_pk_mul_f32 v[36:37], v[76:77], v[76:77]
	v_pk_mul_f32 v[40:41], v[38:39], v[38:39]
	v_fmac_f32_e32 v72, 0xba800000, v58
	v_pk_mov_b32 v[52:53], v[40:41], v[36:37] op_sel:[1,0]
	v_mov_b32_e32 v41, v37
	v_pk_add_f32 v[36:37], v[52:53], v[40:41]
	v_fmamk_f32 v40, v58, 0xba800000, v70
	v_pk_add_f32 v[52:53], v[36:37], v[36:37] op_sel_hi:[0,1]
	v_fmamk_f32 v41, v58, 0xba800000, v71
	v_mul_f32_e32 v36, v40, v40
	v_fmamk_f32 v73, v58, 0xba800000, v73
	v_pk_fma_f32 v[54:55], v[40:41], v[40:41], v[36:37] op_sel_hi:[1,1,0]
	v_mul_f32_e32 v36, v72, v72
	v_pk_fma_f32 v[56:57], v[72:73], v[72:73], v[36:37] op_sel_hi:[1,1,0]
	v_fmamk_f32 v37, v58, 0xba800000, v69
	v_fmamk_f32 v36, v58, 0xba800000, v68
	v_fmamk_f32 v67, v58, 0xba800000, v67
	v_fmac_f32_e32 v66, 0xba800000, v58
	v_mul_f32_e32 v54, v66, v66
	v_mul_f32_e32 v56, v67, v67
	v_mul_f32_e32 v50, v36, v36
	v_mul_f32_e32 v52, v37, v37
	v_pk_add_f32 v[54:55], v[54:55], v[56:57]
	v_pk_add_f32 v[50:51], v[50:51], v[52:53]
	s_nop 0
	v_pk_add_f32 v[50:51], v[54:55], v[50:51]
	s_nop 0
	v_add_f32_e32 v50, v50, v51
	s_waitcnt lgkmcnt(0)
	s_nop 1
	v_add_f32_dpp v51, v59, v59 quad_perm:[1,0,3,2] row_mask:0xf bank_mask:0xf
	s_waitcnt lgkmcnt(1)
	s_nop 1
	v_add_f32_dpp v50, v50, v50 quad_perm:[1,0,3,2] row_mask:0xf bank_mask:0xf
	s_waitcnt lgkmcnt(0)
	s_nop 1
	v_add_f32_dpp v51, v51, v51 quad_perm:[2,3,0,1] row_mask:0xf bank_mask:0xf
	s_waitcnt lgkmcnt(1)
	s_nop 1
	v_add_f32_dpp v50, v50, v50 quad_perm:[2,3,0,1] row_mask:0xf bank_mask:0xf
	s_waitcnt lgkmcnt(0)
	s_nop 1
	v_add_f32_dpp v51, v51, v51 row_half_mirror row_mask:0xf bank_mask:0xf
	s_waitcnt lgkmcnt(1)
	s_nop 1
	v_add_f32_dpp v50, v50, v50 row_half_mirror row_mask:0xf bank_mask:0xf
	s_waitcnt lgkmcnt(0)
	s_nop 1
	v_add_f32_dpp v51, v51, v51 row_mirror row_mask:0xf bank_mask:0xf
	s_waitcnt lgkmcnt(1)
	s_nop 1
	v_add_f32_dpp v50, v50, v50 row_mirror row_mask:0xf bank_mask:0xf
	s_waitcnt lgkmcnt(0)
	s_waitcnt lgkmcnt(1)
	v_mov_b32_e32 v52, v50
	s_waitcnt lgkmcnt(0)
	s_nop 0
	v_readlane_b32 s98, v51, 0
	v_readlane_b32 s99, v51, 16
	v_readlane_b32 s100, v51, 32
	v_readlane_b32 s101, v51, 48
	v_mov_b32_e32 v50, s98
	v_add_f32_e32 v50, s99, v50
	v_mov_b32_e32 v53, s100
	v_add_f32_e32 v53, s101, v53
	v_add_f32_e32 v50, v50, v53
	v_mov_b32_e32 v51, 0x3727c5ac
	v_fmamk_f32 v50, v50, 0x3a800000, v51
	v_mul_f32_e32 v53, 0x4f800000, v50
	v_cmp_gt_f32_e32 vcc, s11, v50
	s_waitcnt lgkmcnt(0)
; __device__ __forceinline__ unsigned pk2(float lo, float hi) { unsigned r; asm("v_cvt_pk_bf16_f32 %0, %1, %2" : "=v"(r) : "v"(lo), "v"(hi)); return r; }
; __device__ __forceinline__ void ln_panel(const float* src, float* dst, bf16_t* dstb, const float* gam, const float* bet, LAS f32x2* T) {
;     ...
;         for (int b = 0; b < NB; ++b) {
;             const float rstd = 1.f / sqrtf(s2[b] * (1.f / DM) + LN_EPS);
;             if (T && lane == 0) T[r + b] = (f32x2){s[b] * (1.f / DM), rstd};
; #pragma unroll
;             for (int j = 0; j < 4; ++j) {
;                 const f32x4 o = cur[b][j] * rstd * gv[j] + bv[j];
;                 if (dst) ((f32x4*)(dst + (size_t)(r + b) * DM))[lane + 64 * j] = o;
;                 if (dstb) { u32x2 w; w.x = pk2(o.x, o.y); w.y = pk2(o.z, o.w); ((u32x2*)(dstb + (size_t)(r + b) * DM))[lane + 64 * j] = w; }
; __global__ void __launch_bounds__(512, 2) fwd_megakernel(Args a) {
;     ...
;     grid.sync();
	s_nop 0
	v_readlane_b32 s98, v52, 0
	v_readlane_b32 s99, v52, 16
	v_readlane_b32 s100, v52, 32
	v_readlane_b32 s101, v52, 48
	v_mov_b32_e32 v54, s98
	v_add_f32_e32 v54, s99, v54
	v_add_f32_e32 v54, s100, v54
	v_add_f32_e32 v54, s101, v54
	v_cndmask_b32_e32 v50, v50, v53, vcc
	v_sqrt_f32_e32 v53, v50
	s_nop 0
	v_add_u32_e32 v55, -1, v53
	v_fma_f32 v56, -v55, v53, v50
	v_cmp_ge_f32_e64 s[4:5], 0, v56
	v_add_u32_e32 v56, 1, v53
	s_nop 0
	v_cndmask_b32_e64 v55, v53, v55, s[4:5]
	v_fma_f32 v53, -v56, v53, v50
	v_cmp_lt_f32_e64 s[4:5], 0, v53
	s_nop 1
	v_cndmask_b32_e64 v53, v55, v56, s[4:5]
	v_mul_f32_e32 v55, 0x37800000, v53
	v_cndmask_b32_e32 v53, v53, v55, vcc
	v_mov_b32_e32 v55, 0x260
	v_cmp_class_f32_e32 vcc, v50, v55
	s_nop 1
	v_cndmask_b32_e32 v50, v53, v50, vcc
	v_div_scale_f32 v53, s[4:5], v50, v50, 1.0
	v_rcp_f32_e32 v56, v53
	s_lshl_b64 s[4:5], s[6:7], 11
	s_add_u32 s6, s8, s4
	s_addc_u32 s7, s9, s5
	v_fma_f32 v57, -v53, v56, 1.0
	v_fmac_f32_e32 v56, v57, v56
	v_div_scale_f32 v57, vcc, 1.0, v50, 1.0
	v_mul_f32_e32 v58, v57, v56
	v_fma_f32 v59, -v53, v58, v57
	v_fmac_f32_e32 v58, v59, v56
	v_fma_f32 v53, -v53, v58, v57
	v_div_fmas_f32 v53, v53, v56, v58
	v_div_fixup_f32 v50, v53, v50, 1.0
	v_pk_mul_f32 v[42:43], v[42:43], v[50:51] op_sel_hi:[1,0]
	v_pk_mul_f32 v[52:53], v[96:97], v[50:51] op_sel_hi:[1,0]
	v_pk_fma_f32 v[42:43], v[26:27], v[42:43], v[30:31]
	v_pk_fma_f32 v[52:53], v[28:29], v[52:53], v[32:33]
	v_cvt_pk_bf16_f32 v42, v42, v43
	s_nop 0
	v_cvt_pk_bf16_f32 v43, v52, v53
	v_lshlrev_b32_e32 v52, 3, v98
	global_store_dwordx2 v52, v[42:43], s[6:7]
	v_pk_mul_f32 v[42:43], v[44:45], v[50:51] op_sel_hi:[1,0]
	v_pk_mul_f32 v[44:45], v[92:93], v[50:51] op_sel_hi:[1,0]
	v_pk_fma_f32 v[42:43], v[18:19], v[42:43], v[22:23]
	v_pk_fma_f32 v[44:45], v[20:21], v[44:45], v[24:25]
	v_cvt_pk_bf16_f32 v42, v42, v43
	s_nop 0
	v_cvt_pk_bf16_f32 v43, v44, v45
	global_store_dwordx2 v52, v[42:43], s[6:7] offset:512
	v_pk_mul_f32 v[42:43], v[46:47], v[50:51] op_sel_hi:[1,0]
	v_pk_mul_f32 v[44:45], v[88:89], v[50:51] op_sel_hi:[1,0]
	v_pk_fma_f32 v[42:43], v[10:11], v[42:43], v[14:15]
	v_pk_fma_f32 v[44:45], v[12:13], v[44:45], v[16:17]
	v_cvt_pk_bf16_f32 v42, v42, v43
	s_nop 0
	v_cvt_pk_bf16_f32 v43, v44, v45
	global_store_dwordx2 v52, v[42:43], s[6:7] offset:1024
	v_pk_mul_f32 v[42:43], v[82:83], v[50:51] op_sel_hi:[1,0]
	v_fmac_f32_e32 v51, 0x3a800000, v54
	v_mul_f32_e32 v44, 0x4f800000, v51
	v_cmp_gt_f32_e32 vcc, s11, v51
	v_pk_fma_f32 v[42:43], v[2:3], v[42:43], v[6:7]
	s_nop 0
	v_cndmask_b32_e32 v46, v51, v44, vcc
	v_sqrt_f32_e32 v47, v46
	v_pk_mul_f32 v[44:45], v[48:49], v[50:51] op_sel_hi:[1,0]
	v_cvt_pk_bf16_f32 v42, v42, v43
	v_add_u32_e32 v48, -1, v47
	v_fma_f32 v49, -v48, v47, v46
	v_cmp_ge_f32_e64 s[4:5], 0, v49
	v_add_u32_e32 v49, 1, v47
	v_pk_fma_f32 v[44:45], v[4:5], v[44:45], v[8:9]
	v_cndmask_b32_e64 v48, v47, v48, s[4:5]
	v_fma_f32 v47, -v49, v47, v46
	v_cmp_lt_f32_e64 s[4:5], 0, v47
	v_cvt_pk_bf16_f32 v43, v44, v45
	global_store_dwordx2 v52, v[42:43], s[6:7] offset:1536
	s_nop 0
	v_cndmask_b32_e64 v47, v48, v49, s[4:5]
	v_mul_f32_e32 v48, 0x37800000, v47
	v_cndmask_b32_e32 v47, v47, v48, vcc
	v_cmp_class_f32_e32 vcc, v46, v55
	s_nop 1
	v_cndmask_b32_e32 v46, v47, v46, vcc
	v_div_scale_f32 v47, s[4:5], v46, v46, 1.0
	v_rcp_f32_e32 v48, v47
	s_or_b32 s4, s1, 31
	s_ashr_i32 s5, s4, 31
	s_lshl_b64 s[4:5], s[4:5], 11
	v_fma_f32 v42, -v47, v48, 1.0
	v_fmac_f32_e32 v48, v42, v48
	v_div_scale_f32 v42, vcc, 1.0, v46, 1.0
	v_mul_f32_e32 v43, v42, v48
	v_fma_f32 v44, -v47, v43, v42
	v_fmac_f32_e32 v43, v44, v48
	v_fma_f32 v42, -v47, v43, v42
	v_div_fmas_f32 v42, v42, v48, v43
	v_div_fixup_f32 v42, v42, v46, 1.0
	v_pk_mul_f32 v[34:35], v[34:35], v[42:43] op_sel_hi:[1,0]
	s_add_u32 s4, s8, s4
	v_pk_mul_f32 v[44:45], v[80:81], v[42:43] op_sel_hi:[1,0]
	v_pk_fma_f32 v[26:27], v[26:27], v[34:35], v[30:31]
	s_addc_u32 s5, s9, s5
	v_pk_fma_f32 v[28:29], v[28:29], v[44:45], v[32:33]
	v_cvt_pk_bf16_f32 v26, v26, v27
	s_movk_i32 s1, 0x3ff
	v_cvt_pk_bf16_f32 v27, v28, v29
	global_store_dwordx2 v52, v[26:27], s[4:5]
	v_pk_mul_f32 v[26:27], v[38:39], v[42:43] op_sel_hi:[1,0]
	v_pk_mul_f32 v[28:29], v[76:77], v[42:43] op_sel_hi:[1,0]
	v_pk_fma_f32 v[18:19], v[18:19], v[26:27], v[22:23]
	v_pk_fma_f32 v[20:21], v[20:21], v[28:29], v[24:25]
	v_cvt_pk_bf16_f32 v18, v18, v19
	s_nop 0
	v_cvt_pk_bf16_f32 v19, v20, v21
	global_store_dwordx2 v52, v[18:19], s[4:5] offset:512
	v_pk_mul_f32 v[18:19], v[40:41], v[42:43] op_sel_hi:[1,0]
	v_pk_mul_f32 v[20:21], v[72:73], v[42:43] op_sel_hi:[1,0]
	v_pk_fma_f32 v[10:11], v[10:11], v[18:19], v[14:15]
	v_pk_fma_f32 v[12:13], v[12:13], v[20:21], v[16:17]
	v_cvt_pk_bf16_f32 v10, v10, v11
	s_nop 0
	v_cvt_pk_bf16_f32 v11, v12, v13
	global_store_dwordx2 v52, v[10:11], s[4:5] offset:1024
	v_pk_mul_f32 v[10:11], v[66:67], v[42:43] op_sel_hi:[1,0]
	v_pk_mul_f32 v[12:13], v[36:37], v[42:43] op_sel_hi:[1,0]
	v_pk_fma_f32 v[2:3], v[2:3], v[10:11], v[6:7]
	v_pk_fma_f32 v[4:5], v[4:5], v[12:13], v[8:9]
	v_cvt_pk_bf16_f32 v2, v2, v3
	s_nop 0
	v_cvt_pk_bf16_f32 v3, v4, v5
	global_store_dwordx2 v52, v[2:3], s[4:5] offset:1536
	v_lshrrev_b32_e32 v2, 20, v0
	v_lshrrev_b32_e32 v0, 10, v0
	v_or_b32_e32 v0, v0, v2
	v_and_or_b32 v0, v0, s1, v189
	v_cmp_eq_u32_e32 vcc, 0, v0
	s_barrier
	s_and_saveexec_b64 s[4:5], vcc
	s_cbranch_execz .LBB0_118
	buffer_wbl2 sc1
	s_waitcnt vmcnt(0)
	s_load_dwordx2 s[6:7], s[22:23], 0x58
	v_mov_b32_e32 v3, 0
	s_mov_b64 s[8:9], exec
	v_mbcnt_lo_u32_b32 v2, s8, 0
	v_mbcnt_hi_u32_b32 v2, s9, v2
	s_waitcnt lgkmcnt(0)
	global_load_dword v0, v3, s[6:7] offset:40
	v_cmp_eq_u32_e32 vcc, 0, v2
	s_and_saveexec_b64 s[10:11], vcc
	s_cbranch_execz .LBB0_111
	s_bcnt1_i32_b64 s1, s[8:9]
	v_mov_b32_e32 v4, s1
	global_atomic_add v4, v3, v4, s[6:7] offset:32 sc0

; __device__ __forceinline__ float bflo(unsigned w) { return __uint_as_float(w << 16); }
; __device__ __forceinline__ float bfhi(unsigned w) { return __uint_as_float(w & 0xffff0000u); }
; __device__ __forceinline__ void ln_panel_b(bf16_t* hb, float* outf, const float* gam, const float* bet) {
;     ...
;     for (int it = 0; it < 32 / NB; ++it) {
;         const int r = r0 + it * NB;
;         float v[NB][16];
; #pragma unroll
;         for (int b = 0; b < NB; ++b)
; #pragma unroll
;             for (int j = 0; j < 2; ++j)
; #pragma unroll
;                 for (int k = 0; k < 4; ++k) { v[b][8 * j + 2 * k] = bflo(nxt[b][j][k]); v[b][8 * j + 2 * k + 1] = bfhi(nxt[b][j][k]); }
;         if (it + 1 < 32 / NB) {
; #pragma unroll
;             for (int b = 0; b < NB; ++b)
; #pragma unroll
;                 for (int j = 0; j < 2; ++j) nxt[b][j] = ((const u32x4*)(hb + (size_t)(r + NB + b) * DM))[lane + 64 * j];
;         }
;         float s[NB], s2[NB];
; #pragma unroll
;         for (int b = 0; b < NB; ++b) { s[b] = 0.f;
; #pragma unroll
;             for (int k = 0; k < 16; ++k) s[b] += v[b][k]; }
; #pragma unroll
;         for (int o = 1; o < 64; o <<= 1)
; #pragma unroll
;             for (int b = 0; b < NB; ++b) s[b] += __shfl_xor(s[b], o);
; #pragma unroll
;         for (int b = 0; b < NB; ++b) { const float mean = s[b] * (1.f / DM); s2[b] = 0.f;
; #pragma unroll
;             for (int k = 0; k < 16; ++k) { v[b][k] -= mean; s2[b] += v[b][k] * v[b][k]; } }
.LBB0_425:
	s_waitcnt vmcnt(0)
	v_lshlrev_b32_e32 v0, 16, v34
	v_and_b32_e32 v51, 0xffff0000, v34
	v_add_f32_e32 v86, 0, v0
	v_lshlrev_b32_e32 v56, 16, v35
	v_add_f32_e32 v86, v86, v51
	v_and_b32_e32 v57, 0xffff0000, v35
	v_add_f32_e32 v86, v86, v56
	v_lshlrev_b32_e32 v58, 16, v36
	v_add_f32_e32 v86, v86, v57
	v_and_b32_e32 v59, 0xffff0000, v36
	v_lshlrev_b32_e32 v70, 16, v42
	v_add_f32_e32 v86, v86, v58
	v_lshlrev_b32_e32 v60, 16, v37
	v_and_b32_e32 v71, 0xffff0000, v42
	v_add_f32_e32 v86, v86, v59
	v_add_f32_e32 v87, 0, v70
	v_and_b32_e32 v61, 0xffff0000, v37
	v_lshlrev_b32_e32 v72, 16, v43
	v_add_f32_e32 v86, v86, v60
	v_add_f32_e32 v87, v87, v71
	v_lshlrev_b32_e32 v62, 16, v38
	v_and_b32_e32 v73, 0xffff0000, v43
	v_add_f32_e32 v86, v86, v61
	v_add_f32_e32 v87, v87, v72
	v_and_b32_e32 v63, 0xffff0000, v38
	v_lshlrev_b32_e32 v74, 16, v44
	v_add_f32_e32 v86, v86, v62
	v_add_f32_e32 v87, v87, v73
	v_lshlrev_b32_e32 v64, 16, v39
	v_and_b32_e32 v75, 0xffff0000, v44
	v_add_f32_e32 v86, v86, v63
	v_add_f32_e32 v87, v87, v74
	v_and_b32_e32 v65, 0xffff0000, v39
	v_lshlrev_b32_e32 v76, 16, v45
	v_add_f32_e32 v86, v86, v64
	v_add_f32_e32 v87, v87, v75
	v_lshlrev_b32_e32 v66, 16, v40
	v_and_b32_e32 v77, 0xffff0000, v45
	v_add_f32_e32 v86, v86, v65
	v_add_f32_e32 v87, v87, v76
	v_and_b32_e32 v67, 0xffff0000, v40
	v_lshlrev_b32_e32 v78, 16, v46
	v_add_f32_e32 v86, v86, v66
	v_add_f32_e32 v87, v87, v77
	v_lshlrev_b32_e32 v68, 16, v41
	v_and_b32_e32 v79, 0xffff0000, v46
	v_add_f32_e32 v86, v86, v67
	v_add_f32_e32 v87, v87, v78
	v_and_b32_e32 v69, 0xffff0000, v41
	v_lshlrev_b32_e32 v80, 16, v47
	v_add_f32_e32 v86, v86, v68
	v_add_f32_e32 v87, v87, v79
	v_and_b32_e32 v81, 0xffff0000, v47
	v_add_f32_e32 v86, v86, v69
	v_add_f32_e32 v87, v87, v80
	v_lshlrev_b32_e32 v82, 16, v48
	v_add_f32_e32 v87, v87, v81
	v_and_b32_e32 v83, 0xffff0000, v48
	v_add_f32_e32 v87, v87, v82
	v_lshlrev_b32_e32 v84, 16, v49
	v_add_f32_e32 v87, v87, v83
	v_and_b32_e32 v85, 0xffff0000, v49
	v_add_f32_e32 v87, v87, v84
	v_add_f32_e32 v87, v87, v85
	s_waitcnt lgkmcnt(0)
	s_nop 1
	v_add_f32_dpp v86, v86, v86 quad_perm:[1,0,3,2] row_mask:0xf bank_mask:0xf
	v_lshl_add_u64 v[54:55], v[52:53], 0, s[26:27]
	s_mov_b32 s1, 0x6001000
	v_add_co_u32_e32 v46, vcc, s1, v54
	s_waitcnt lgkmcnt(0)
	s_nop 1
	v_add_f32_dpp v87, v87, v87 quad_perm:[1,0,3,2] row_mask:0xf bank_mask:0xf
	v_addc_co_u32_e32 v47, vcc, 0, v55, vcc
	global_load_dwordx4 v[34:37], v[46:47], off
	global_load_dwordx4 v[38:41], v[46:47], off offset:1024
	global_load_dwordx4 v[42:45], v[46:47], off offset:2048
	s_nop 0
	global_load_dwordx4 v[46:49], v[46:47], off offset:3072
	s_mov_b32 s1, 0x6000000
	s_waitcnt lgkmcnt(0)
	s_nop 1
	v_add_f32_dpp v86, v86, v86 quad_perm:[2,3,0,1] row_mask:0xf bank_mask:0xf
	s_add_u32 s26, s26, 0x1000
	s_addc_u32 s27, s27, 0
	s_cmpk_lg_u32 s26, 0xf000
	s_waitcnt lgkmcnt(0)
	s_nop 1
	v_add_f32_dpp v87, v87, v87 quad_perm:[2,3,0,1] row_mask:0xf bank_mask:0xf
	s_waitcnt lgkmcnt(0)
	s_nop 1
	v_add_f32_dpp v86, v86, v86 row_half_mirror row_mask:0xf bank_mask:0xf
	s_waitcnt lgkmcnt(0)
	s_nop 1
	v_add_f32_dpp v87, v87, v87 row_half_mirror row_mask:0xf bank_mask:0xf
	s_waitcnt lgkmcnt(0)
	s_nop 1
	v_add_f32_dpp v86, v86, v86 row_mirror row_mask:0xf bank_mask:0xf
	s_waitcnt lgkmcnt(0)
	s_nop 1
	v_add_f32_dpp v87, v87, v87 row_mirror row_mask:0xf bank_mask:0xf
	s_waitcnt lgkmcnt(0)
	s_waitcnt lgkmcnt(0)
	s_waitcnt lgkmcnt(0)
	s_nop 0
	v_readlane_b32 s98, v86, 0
	v_readlane_b32 s99, v86, 16
	v_readlane_b32 s100, v86, 32
	v_readlane_b32 s101, v86, 48
	v_mov_b32_e32 v86, s98
	v_add_f32_e32 v86, s99, v86
	v_mov_b32_e32 v88, s100
	v_add_f32_e32 v88, s101, v88
	v_add_f32_e32 v86, v86, v88
	v_fmac_f32_e32 v51, 0xba800000, v86
	v_fmac_f32_e32 v0, 0xba800000, v86
	v_fmac_f32_e32 v56, 0xba800000, v86
	v_fmac_f32_e32 v57, 0xba800000, v86
	s_waitcnt lgkmcnt(0)
	s_nop 0
	v_readlane_b32 s98, v87, 0
	v_readlane_b32 s99, v87, 16
	v_readlane_b32 s100, v87, 32
	v_readlane_b32 s101, v87, 48
	v_mov_b32_e32 v87, s98
	v_add_f32_e32 v87, s99, v87
	v_mov_b32_e32 v88, s100
	v_add_f32_e32 v88, s101, v88
	v_add_f32_e32 v87, v87, v88
	v_mul_f32_e32 v88, v51, v51
	v_fmac_f32_e32 v88, v0, v0
	v_fmac_f32_e32 v88, v56, v56
	v_fmac_f32_e32 v88, v57, v57
	v_fmac_f32_e32 v58, 0xba800000, v86
	v_fmac_f32_e32 v88, v58, v58
	v_fmac_f32_e32 v59, 0xba800000, v86
	v_fmac_f32_e32 v71, 0xba800000, v87
	v_fmac_f32_e32 v88, v59, v59
	v_fmac_f32_e32 v60, 0xba800000, v86
	v_fmac_f32_e32 v61, 0xba800000, v86
	v_fmac_f32_e32 v62, 0xba800000, v86
	v_fmac_f32_e32 v63, 0xba800000, v86
	v_fmac_f32_e32 v64, 0xba800000, v86
	v_fmac_f32_e32 v65, 0xba800000, v86
	v_fmac_f32_e32 v66, 0xba800000, v86
	v_fmac_f32_e32 v67, 0xba800000, v86
	v_fmac_f32_e32 v68, 0xba800000, v86
	v_fmac_f32_e32 v69, 0xba800000, v86
	v_fmac_f32_e32 v70, 0xba800000, v87
	v_mul_f32_e32 v86, v71, v71
	v_fmac_f32_e32 v88, v60, v60
	v_fmac_f32_e32 v86, v70, v70
	v_fmac_f32_e32 v72, 0xba800000, v87
	v_fmac_f32_e32 v88, v61, v61
	v_fmac_f32_e32 v86, v72, v72
	v_fmac_f32_e32 v73, 0xba800000, v87
	v_fmac_f32_e32 v88, v62, v62
	v_fmac_f32_e32 v86, v73, v73
	v_fmac_f32_e32 v74, 0xba800000, v87
	v_fmac_f32_e32 v88, v63, v63
	v_fmac_f32_e32 v86, v74, v74
	v_fmac_f32_e32 v75, 0xba800000, v87
	v_fmac_f32_e32 v88, v64, v64
	v_fmac_f32_e32 v86, v75, v75
	v_fmac_f32_e32 v76, 0xba800000, v87
	v_fmac_f32_e32 v88, v65, v65
	v_fmac_f32_e32 v86, v76, v76
	v_fmac_f32_e32 v77, 0xba800000, v87
	v_fmac_f32_e32 v88, v66, v66
	v_fmac_f32_e32 v86, v77, v77
	v_fmac_f32_e32 v78, 0xba800000, v87
	v_fmac_f32_e32 v88, v67, v67
	v_fmac_f32_e32 v86, v78, v78
	v_fmac_f32_e32 v79, 0xba800000, v87
	v_fmac_f32_e32 v88, v68, v68
	v_fmac_f32_e32 v86, v79, v79
	v_fmac_f32_e32 v80, 0xba800000, v87
	v_fmac_f32_e32 v88, v69, v69
	v_fmac_f32_e32 v86, v80, v80
	v_fmac_f32_e32 v81, 0xba800000, v87
	v_fmac_f32_e32 v86, v81, v81
	v_fmac_f32_e32 v82, 0xba800000, v87
	v_fmac_f32_e32 v83, 0xba800000, v87
	v_fmac_f32_e32 v84, 0xba800000, v87
	v_fmac_f32_e32 v85, 0xba800000, v87
	v_fmac_f32_e32 v86, v82, v82
	v_fmac_f32_e32 v86, v83, v83
	v_fmac_f32_e32 v86, v84, v84
	v_fmac_f32_e32 v86, v85, v85
	s_waitcnt lgkmcnt(0)
; __device__ __forceinline__ unsigned pk2(float lo, float hi) { unsigned r; asm("v_cvt_pk_bf16_f32 %0, %1, %2" : "=v"(r) : "v"(lo), "v"(hi)); return r; }
; __device__ __forceinline__ void ln_panel_b(bf16_t* hb, float* outf, const float* gam, const float* bet) {
;     ...
;         for (int o = 1; o < 64; o <<= 1)
; #pragma unroll
;             for (int b = 0; b < NB; ++b) s2[b] += __shfl_xor(s2[b], o);
; #pragma unroll
;         for (int b = 0; b < NB; ++b) {
;             const float rstd = 1.f / sqrtf(s2[b] * (1.f / DM) + LN_EPS);
; #pragma unroll
;             for (int j = 0; j < 2; ++j) {
;                 float o[8];
; #pragma unroll
;                 for (int k = 0; k < 8; ++k) o[k] = v[b][8 * j + k] * rstd * gv[j][k >> 2][k & 3] + bv[j][k >> 2][k & 3];
;                 if (outf) { f32x4* op = (f32x4*)(outf + (size_t)(r + b) * DM + 512 * j + 8 * lane); op[0] = (f32x4){o[0], o[1], o[2], o[3]}; op[1] = (f32x4){o[4], o[5], o[6], o[7]}; }
;                 else { u32x4 w; w.x = pk2(o[0], o[1]); w.y = pk2(o[2], o[3]); w.z = pk2(o[4], o[5]); w.w = pk2(o[6], o[7]); ((u32x4*)(hb + (size_t)(r + b) * DM))[lane + 64 * j] = w; }
;             }
	s_nop 1
	v_add_f32_dpp v87, v88, v88 quad_perm:[1,0,3,2] row_mask:0xf bank_mask:0xf
	s_waitcnt lgkmcnt(0)
	s_nop 1
	v_add_f32_dpp v86, v86, v86 quad_perm:[1,0,3,2] row_mask:0xf bank_mask:0xf
	s_waitcnt lgkmcnt(0)
	s_nop 1
	v_add_f32_dpp v87, v87, v87 quad_perm:[2,3,0,1] row_mask:0xf bank_mask:0xf
	s_waitcnt lgkmcnt(0)
	s_nop 1
	v_add_f32_dpp v86, v86, v86 quad_perm:[2,3,0,1] row_mask:0xf bank_mask:0xf
	s_waitcnt lgkmcnt(0)
	s_nop 1
	v_add_f32_dpp v87, v87, v87 row_half_mirror row_mask:0xf bank_mask:0xf
	s_waitcnt lgkmcnt(0)
	s_nop 1
	v_add_f32_dpp v86, v86, v86 row_half_mirror row_mask:0xf bank_mask:0xf
	s_waitcnt lgkmcnt(0)
	s_nop 1
	v_add_f32_dpp v87, v87, v87 row_mirror row_mask:0xf bank_mask:0xf
	s_waitcnt lgkmcnt(0)
	s_nop 1
	v_add_f32_dpp v86, v86, v86 row_mirror row_mask:0xf bank_mask:0xf
	s_waitcnt lgkmcnt(0)
	s_waitcnt lgkmcnt(0)
	s_waitcnt lgkmcnt(0)
	s_nop 0
	v_readlane_b32 s98, v87, 0
	v_readlane_b32 s99, v87, 16
	v_readlane_b32 s100, v87, 32
	v_readlane_b32 s101, v87, 48
	v_mov_b32_e32 v87, s98
	v_add_f32_e32 v87, s99, v87
	v_mov_b32_e32 v88, s100
	v_add_f32_e32 v88, s101, v88
	v_add_f32_e32 v87, v87, v88
	v_fmamk_f32 v87, v87, 0x3a800000, v231
	v_cmp_gt_f32_e32 vcc, s97, v87
	s_waitcnt lgkmcnt(0)
	s_nop 0
	v_readlane_b32 s98, v86, 0
	v_readlane_b32 s99, v86, 16
	v_readlane_b32 s100, v86, 32
	v_readlane_b32 s101, v86, 48
	v_mov_b32_e32 v86, s98
	v_add_f32_e32 v86, s99, v86
	v_mov_b32_e32 v88, s100
	v_add_f32_e32 v88, s101, v88
	v_add_f32_e32 v86, v86, v88
	v_mul_f32_e32 v88, 0x4f800000, v87
	v_cndmask_b32_e32 v87, v87, v88, vcc
	v_sqrt_f32_e32 v88, v87
	s_nop 0
	v_add_u32_e32 v89, -1, v88
	v_fma_f32 v90, -v89, v88, v87
	v_cmp_ge_f32_e64 s[2:3], 0, v90
	v_add_u32_e32 v90, 1, v88
	s_nop 0
	v_cndmask_b32_e64 v89, v88, v89, s[2:3]
	v_fma_f32 v88, -v90, v88, v87
	v_cmp_lt_f32_e64 s[2:3], 0, v88
	s_nop 1
	v_cndmask_b32_e64 v88, v89, v90, s[2:3]
	v_mul_f32_e32 v89, 0x37800000, v88
	v_cndmask_b32_e32 v88, v88, v89, vcc
	v_cmp_class_f32_e32 vcc, v87, v232
	s_nop 1
	v_cndmask_b32_e32 v87, v88, v87, vcc
	v_div_scale_f32 v88, s[2:3], v87, v87, 1.0
	v_rcp_f32_e32 v89, v88
	s_nop 0
	v_fma_f32 v90, -v88, v89, 1.0
	v_fmac_f32_e32 v89, v90, v89
	v_div_scale_f32 v90, vcc, 1.0, v87, 1.0
	v_mul_f32_e32 v91, v90, v89
	v_fma_f32 v92, -v88, v91, v90
	v_fmac_f32_e32 v91, v92, v89
	v_fma_f32 v88, -v88, v91, v90
	v_div_fmas_f32 v88, v88, v89, v91
	v_div_fixup_f32 v87, v88, v87, 1.0
	v_mul_f32_e32 v56, v56, v87
	v_fma_f32 v88, v32, v56, v24
	v_mul_f32_e32 v56, v57, v87
	v_fma_f32 v57, v33, v56, v25
	v_mul_f32_e32 v56, v58, v87
	v_fma_f32 v58, v26, v56, v18
	v_mul_f32_e32 v56, v59, v87
	v_fma_f32 v59, v27, v56, v19
	v_mul_f32_e32 v56, v60, v87
	v_fma_f32 v60, v28, v56, v20
	v_mul_f32_e32 v56, v61, v87
	v_mul_f32_e32 v0, v0, v87
	v_mul_f32_e32 v51, v51, v87
	v_fma_f32 v61, v29, v56, v21
	v_cvt_pk_bf16_f32 v58, v58, v59
	v_cvt_pk_bf16_f32 v59, v60, v61
	v_add_co_u32_e32 v60, vcc, s1, v54
	v_mul_f32_e32 v54, v64, v87
	v_fma_f32 v0, v30, v0, v22
	v_fma_f32 v51, v31, v51, v23
	v_cvt_pk_bf16_f32 v56, v0, v51
	v_addc_co_u32_e32 v61, vcc, 0, v55, vcc
	v_fma_f32 v55, v16, v54, v8
	v_mul_f32_e32 v54, v65, v87
	v_cvt_pk_bf16_f32 v57, v88, v57
	global_store_dwordx4 v[60:61], v[56:59], off
	v_mul_f32_e32 v0, v62, v87
	v_fma_f32 v0, v14, v0, v6
	v_fma_f32 v56, v17, v54, v9
	v_mul_f32_e32 v54, v66, v87
	v_fma_f32 v57, v10, v54, v2
	v_mul_f32_e32 v54, v67, v87
	v_fma_f32 v58, v11, v54, v3
	v_mul_f32_e32 v54, v68, v87
	v_mul_f32_e32 v51, v63, v87
	v_fma_f32 v59, v12, v54, v4
	v_mul_f32_e32 v54, v69, v87
	v_fma_f32 v51, v15, v51, v7
	v_fma_f32 v62, v13, v54, v5
	v_cvt_pk_bf16_f32 v54, v0, v51
	v_fmamk_f32 v0, v86, 0x3a800000, v231
	v_cmp_gt_f32_e32 vcc, s97, v0
	v_mul_f32_e32 v51, 0x4f800000, v0
	v_cvt_pk_bf16_f32 v55, v55, v56
	v_cvt_pk_bf16_f32 v56, v57, v58
	v_cvt_pk_bf16_f32 v57, v59, v62
	global_store_dwordx4 v[60:61], v[54:57], off offset:1024
	v_cndmask_b32_e32 v0, v0, v51, vcc
	v_sqrt_f32_e32 v51, v0
	s_nop 0
	v_add_u32_e32 v54, -1, v51
	v_fma_f32 v55, -v54, v51, v0
	v_cmp_ge_f32_e64 s[2:3], 0, v55
	v_add_u32_e32 v55, 1, v51
	s_nop 0
	v_cndmask_b32_e64 v54, v51, v54, s[2:3]
	v_fma_f32 v51, -v55, v51, v0
	v_cmp_lt_f32_e64 s[2:3], 0, v51
	s_nop 1
	v_cndmask_b32_e64 v51, v54, v55, s[2:3]
	v_mul_f32_e32 v54, 0x37800000, v51
	v_cndmask_b32_e32 v51, v51, v54, vcc
	v_cmp_class_f32_e32 vcc, v0, v232
	s_nop 1
	v_cndmask_b32_e32 v0, v51, v0, vcc
	v_div_scale_f32 v51, s[2:3], v0, v0, 1.0
	v_rcp_f32_e32 v54, v51
	s_nop 0
	v_fma_f32 v55, -v51, v54, 1.0
	v_fmac_f32_e32 v54, v55, v54
	v_div_scale_f32 v55, vcc, 1.0, v0, 1.0
	v_mul_f32_e32 v56, v55, v54
	v_fma_f32 v57, -v51, v56, v55
	v_fmac_f32_e32 v56, v57, v54
	v_fma_f32 v51, -v51, v56, v55
	v_div_fmas_f32 v51, v51, v54, v56
	v_div_fixup_f32 v0, v51, v0, 1.0
	v_mul_f32_e32 v54, v71, v0
	v_mul_f32_e32 v55, v72, v0
	v_mul_f32_e32 v56, v73, v0
	v_mul_f32_e32 v57, v74, v0
	v_mul_f32_e32 v51, v70, v0
	v_fma_f32 v54, v31, v54, v23
	v_fma_f32 v55, v32, v55, v24
	v_fma_f32 v56, v33, v56, v25
	v_fma_f32 v57, v26, v57, v18
	v_mul_f32_e32 v58, v75, v0
	v_mul_f32_e32 v59, v76, v0
	v_mul_f32_e32 v62, v77, v0
	v_fma_f32 v51, v30, v51, v22
	v_fma_f32 v58, v27, v58, v19
	v_fma_f32 v59, v28, v59, v20
	v_fma_f32 v62, v29, v62, v21
	v_cvt_pk_bf16_f32 v54, v51, v54
	v_cvt_pk_bf16_f32 v55, v55, v56
	v_cvt_pk_bf16_f32 v56, v57, v58
	v_cvt_pk_bf16_f32 v57, v59, v62
	global_store_dwordx4 v[60:61], v[54:57], off offset:2048
	v_mul_f32_e32 v51, v78, v0
	v_mul_f32_e32 v58, v83, v0
	v_mul_f32_e32 v54, v79, v0
	v_mul_f32_e32 v55, v80, v0
	v_mul_f32_e32 v56, v81, v0
	v_mul_f32_e32 v57, v82, v0
	v_fma_f32 v54, v15, v54, v7
	v_fma_f32 v55, v16, v55, v8
	v_fma_f32 v56, v17, v56, v9
	v_fma_f32 v57, v10, v57, v2
	v_mul_f32_e32 v59, v84, v0
	v_mul_f32_e32 v0, v85, v0
	v_fma_f32 v51, v14, v51, v6
	v_fma_f32 v58, v11, v58, v3
	v_fma_f32 v59, v12, v59, v4
	v_fma_f32 v0, v13, v0, v5
	v_cvt_pk_bf16_f32 v54, v51, v54
	v_cvt_pk_bf16_f32 v55, v55, v56
	v_cvt_pk_bf16_f32 v56, v57, v58
	v_cvt_pk_bf16_f32 v57, v59, v0
	global_store_dwordx4 v[60:61], v[54:57], off offset:3072
	s_cbranch_scc1 .LBB0_425
; __device__ __forceinline__ float bflo(unsigned w) { return __uint_as_float(w << 16); }
; __device__ __forceinline__ float bfhi(unsigned w) { return __uint_as_float(w & 0xffff0000u); }
; __device__ __forceinline__ void ln_panel_b(bf16_t* hb, float* outf, const float* gam, const float* bet) {
;     ...
; #pragma unroll
;         for (int b = 0; b < NB; ++b)
; #pragma unroll
;             for (int j = 0; j < 2; ++j)
; #pragma unroll
;                 for (int k = 0; k < 4; ++k) { v[b][8 * j + 2 * k] = bflo(nxt[b][j][k]); v[b][8 * j + 2 * k + 1] = bfhi(nxt[b][j][k]); }
;         if (it + 1 < 32 / NB) {
; #pragma unroll
;             for (int b = 0; b < NB; ++b)
; #pragma unroll
;                 for (int j = 0; j < 2; ++j) nxt[b][j] = ((const u32x4*)(hb + (size_t)(r + NB + b) * DM))[lane + 64 * j];
;         }
;         float s[NB], s2[NB];
; #pragma unroll
;         for (int b = 0; b < NB; ++b) { s[b] = 0.f;
; #pragma unroll
;             for (int k = 0; k < 16; ++k) s[b] += v[b][k]; }
; #pragma unroll
;         for (int o = 1; o < 64; o <<= 1)
; #pragma unroll
;             for (int b = 0; b < NB; ++b) s[b] += __shfl_xor(s[b], o);
; #pragma unroll
;         for (int b = 0; b < NB; ++b) { const float mean = s[b] * (1.f / DM); s2[b] = 0.f;
; #pragma unroll
;             for (int k = 0; k < 16; ++k) { v[b][k] -= mean; s2[b] += v[b][k] * v[b][k]; } }
	s_waitcnt vmcnt(7)
	v_and_b32_e32 v65, 0xffff0000, v34
	v_lshlrev_b32_e32 v34, 16, v34
	v_add_f32_e32 v66, 0, v34
	v_and_b32_e32 v64, 0xffff0000, v35
	v_lshlrev_b32_e32 v35, 16, v35
	v_add_f32_e32 v66, v66, v65
	v_add_f32_e32 v66, v66, v35
	v_and_b32_e32 v63, 0xffff0000, v36
	v_lshlrev_b32_e32 v36, 16, v36
	v_add_f32_e32 v66, v66, v64
	s_waitcnt vmcnt(5)
	v_and_b32_e32 v57, 0xffff0000, v42
	v_lshlrev_b32_e32 v42, 16, v42
	v_add_f32_e32 v66, v66, v36
	v_and_b32_e32 v62, 0xffff0000, v37
	v_lshlrev_b32_e32 v37, 16, v37
	v_add_f32_e32 v66, v66, v63
	v_add_f32_e32 v67, 0, v42
	v_and_b32_e32 v56, 0xffff0000, v43
	v_lshlrev_b32_e32 v43, 16, v43
	v_add_f32_e32 v66, v66, v37
	v_add_f32_e32 v67, v67, v57
	v_and_b32_e32 v61, 0xffff0000, v38
	v_lshlrev_b32_e32 v38, 16, v38
	v_add_f32_e32 v66, v66, v62
	v_add_f32_e32 v67, v67, v43
	v_and_b32_e32 v55, 0xffff0000, v44
	v_lshlrev_b32_e32 v44, 16, v44
	v_add_f32_e32 v66, v66, v38
	v_add_f32_e32 v67, v67, v56
	v_and_b32_e32 v60, 0xffff0000, v39
	v_lshlrev_b32_e32 v39, 16, v39
	v_add_f32_e32 v66, v66, v61
	v_add_f32_e32 v67, v67, v44
	v_and_b32_e32 v54, 0xffff0000, v45
	v_lshlrev_b32_e32 v45, 16, v45
	v_add_f32_e32 v66, v66, v39
	v_add_f32_e32 v67, v67, v55
	v_and_b32_e32 v59, 0xffff0000, v40
	v_lshlrev_b32_e32 v40, 16, v40
	v_add_f32_e32 v66, v66, v60
	v_add_f32_e32 v67, v67, v45
	s_waitcnt vmcnt(4)
	v_and_b32_e32 v53, 0xffff0000, v46
	v_lshlrev_b32_e32 v46, 16, v46
	v_add_f32_e32 v66, v66, v40
	v_add_f32_e32 v67, v67, v54
	v_and_b32_e32 v58, 0xffff0000, v41
	v_lshlrev_b32_e32 v41, 16, v41
	v_add_f32_e32 v66, v66, v59
	v_add_f32_e32 v67, v67, v46
	v_and_b32_e32 v52, 0xffff0000, v47
	v_lshlrev_b32_e32 v47, 16, v47
	v_add_f32_e32 v66, v66, v41
	v_add_f32_e32 v67, v67, v53
	v_add_f32_e32 v66, v66, v58
	v_add_f32_e32 v67, v67, v47
	v_and_b32_e32 v51, 0xffff0000, v48
	v_lshlrev_b32_e32 v48, 16, v48
	v_add_f32_e32 v67, v67, v52
	v_add_f32_e32 v67, v67, v48
	v_and_b32_e32 v0, 0xffff0000, v49
	v_lshlrev_b32_e32 v49, 16, v49
	v_add_f32_e32 v67, v67, v51
	v_add_f32_e32 v67, v67, v49
	v_add_f32_e32 v67, v67, v0
	s_waitcnt lgkmcnt(0)
	s_nop 1
	v_add_f32_dpp v66, v66, v66 quad_perm:[1,0,3,2] row_mask:0xf bank_mask:0xf
	s_or_b32 s10, s10, 30
	s_ashr_i32 s11, s10, 31
	v_lshlrev_b32_e32 v50, 4, v50
	s_movk_i32 s42, 0x400
	s_waitcnt lgkmcnt(0)
	s_nop 1
	v_add_f32_dpp v67, v67, v67 quad_perm:[1,0,3,2] row_mask:0xf bank_mask:0xf
	v_mov_b32_e32 v131, v1
	v_mov_b32_e32 v135, v1
	v_mov_b32_e32 v133, v1
	s_waitcnt lgkmcnt(0)
	s_nop 1
	v_add_f32_dpp v66, v66, v66 quad_perm:[2,3,0,1] row_mask:0xf bank_mask:0xf
	s_waitcnt lgkmcnt(0)
	s_nop 1
	v_add_f32_dpp v67, v67, v67 quad_perm:[2,3,0,1] row_mask:0xf bank_mask:0xf
	s_waitcnt lgkmcnt(0)
	s_nop 1
	v_add_f32_dpp v66, v66, v66 row_half_mirror row_mask:0xf bank_mask:0xf
	s_waitcnt lgkmcnt(0)
	s_nop 1
	v_add_f32_dpp v67, v67, v67 row_half_mirror row_mask:0xf bank_mask:0xf
	s_waitcnt lgkmcnt(0)
	s_nop 1
	v_add_f32_dpp v66, v66, v66 row_mirror row_mask:0xf bank_mask:0xf
	s_waitcnt lgkmcnt(0)
	s_nop 1
	v_add_f32_dpp v67, v67, v67 row_mirror row_mask:0xf bank_mask:0xf
	s_waitcnt lgkmcnt(0)
	s_waitcnt lgkmcnt(0)
	s_waitcnt lgkmcnt(0)
	s_nop 0
	v_readlane_b32 s98, v66, 0
	v_readlane_b32 s99, v66, 16
	v_readlane_b32 s100, v66, 32
	v_readlane_b32 s101, v66, 48
	v_mov_b32_e32 v66, s98
	v_add_f32_e32 v66, s99, v66
	v_mov_b32_e32 v68, s100
	v_add_f32_e32 v68, s101, v68
	v_add_f32_e32 v66, v66, v68
	v_fmac_f32_e32 v65, 0xba800000, v66
	v_fmac_f32_e32 v34, 0xba800000, v66
	v_fmac_f32_e32 v35, 0xba800000, v66
	v_fmac_f32_e32 v64, 0xba800000, v66
	s_waitcnt lgkmcnt(0)
	s_nop 0
	v_readlane_b32 s98, v67, 0
	v_readlane_b32 s99, v67, 16
	v_readlane_b32 s100, v67, 32
	v_readlane_b32 s101, v67, 48
	v_mov_b32_e32 v67, s98
	v_add_f32_e32 v67, s99, v67
	v_mov_b32_e32 v68, s100
	v_add_f32_e32 v68, s101, v68
	v_add_f32_e32 v67, v67, v68
	v_mul_f32_e32 v68, v65, v65
	v_fmac_f32_e32 v68, v34, v34
	v_fmac_f32_e32 v68, v35, v35
	v_fmac_f32_e32 v68, v64, v64
	v_fmac_f32_e32 v36, 0xba800000, v66
	v_fmac_f32_e32 v68, v36, v36
	v_fmac_f32_e32 v63, 0xba800000, v66
	v_fmac_f32_e32 v57, 0xba800000, v67
	v_fmac_f32_e32 v68, v63, v63
	v_fmac_f32_e32 v37, 0xba800000, v66
	v_fmac_f32_e32 v62, 0xba800000, v66
	v_fmac_f32_e32 v38, 0xba800000, v66
	v_fmac_f32_e32 v61, 0xba800000, v66
	v_fmac_f32_e32 v39, 0xba800000, v66
	v_fmac_f32_e32 v60, 0xba800000, v66
	v_fmac_f32_e32 v40, 0xba800000, v66
	v_fmac_f32_e32 v59, 0xba800000, v66
	v_fmac_f32_e32 v41, 0xba800000, v66
	v_fmac_f32_e32 v58, 0xba800000, v66
	v_fmac_f32_e32 v42, 0xba800000, v67
	v_mul_f32_e32 v66, v57, v57
	v_fmac_f32_e32 v68, v37, v37
	v_fmac_f32_e32 v66, v42, v42
	v_fmac_f32_e32 v43, 0xba800000, v67
	v_fmac_f32_e32 v68, v62, v62
	v_fmac_f32_e32 v66, v43, v43
	v_fmac_f32_e32 v56, 0xba800000, v67
	v_fmac_f32_e32 v68, v38, v38
	v_fmac_f32_e32 v66, v56, v56
	v_fmac_f32_e32 v44, 0xba800000, v67
	v_fmac_f32_e32 v68, v61, v61
	v_fmac_f32_e32 v66, v44, v44
	v_fmac_f32_e32 v55, 0xba800000, v67
	v_fmac_f32_e32 v68, v39, v39
	v_fmac_f32_e32 v66, v55, v55
	v_fmac_f32_e32 v45, 0xba800000, v67
	v_fmac_f32_e32 v68, v60, v60
	v_fmac_f32_e32 v66, v45, v45
	v_fmac_f32_e32 v54, 0xba800000, v67
	v_fmac_f32_e32 v68, v40, v40
	v_fmac_f32_e32 v66, v54, v54
	v_fmac_f32_e32 v46, 0xba800000, v67
	v_fmac_f32_e32 v68, v59, v59
	v_fmac_f32_e32 v66, v46, v46
	v_fmac_f32_e32 v53, 0xba800000, v67
	v_fmac_f32_e32 v68, v41, v41
	v_fmac_f32_e32 v66, v53, v53
	v_fmac_f32_e32 v47, 0xba800000, v67
	v_fmac_f32_e32 v68, v58, v58
	v_fmac_f32_e32 v66, v47, v47
	v_fmac_f32_e32 v52, 0xba800000, v67
	v_fmac_f32_e32 v66, v52, v52
	v_fmac_f32_e32 v48, 0xba800000, v67
	v_fmac_f32_e32 v51, 0xba800000, v67
	v_fmac_f32_e32 v49, 0xba800000, v67
	v_fmac_f32_e32 v0, 0xba800000, v67
	v_fmac_f32_e32 v66, v48, v48
	v_fmac_f32_e32 v66, v51, v51
	v_fmac_f32_e32 v66, v49, v49
	v_fmac_f32_e32 v66, v0, v0
	s_waitcnt lgkmcnt(0)
; __device__ __forceinline__ unsigned pk2(float lo, float hi) { unsigned r; asm("v_cvt_pk_bf16_f32 %0, %1, %2" : "=v"(r) : "v"(lo), "v"(hi)); return r; }
; __device__ __forceinline__ void ln_panel_b(bf16_t* hb, float* outf, const float* gam, const float* bet) {
;     ...
;         for (int o = 1; o < 64; o <<= 1)
; #pragma unroll
;             for (int b = 0; b < NB; ++b) s2[b] += __shfl_xor(s2[b], o);
; #pragma unroll
;         for (int b = 0; b < NB; ++b) {
;             const float rstd = 1.f / sqrtf(s2[b] * (1.f / DM) + LN_EPS);
; #pragma unroll
;             for (int j = 0; j < 2; ++j) {
;                 float o[8];
; #pragma unroll
;                 for (int k = 0; k < 8; ++k) o[k] = v[b][8 * j + k] * rstd * gv[j][k >> 2][k & 3] + bv[j][k >> 2][k & 3];
;                 if (outf) { f32x4* op = (f32x4*)(outf + (size_t)(r + b) * DM + 512 * j + 8 * lane); op[0] = (f32x4){o[0], o[1], o[2], o[3]}; op[1] = (f32x4){o[4], o[5], o[6], o[7]}; }
;                 else { u32x4 w; w.x = pk2(o[0], o[1]); w.y = pk2(o[2], o[3]); w.z = pk2(o[4], o[5]); w.w = pk2(o[6], o[7]); ((u32x4*)(hb + (size_t)(r + b) * DM))[lane + 64 * j] = w; }
;             }
	s_nop 1
	v_add_f32_dpp v67, v68, v68 quad_perm:[1,0,3,2] row_mask:0xf bank_mask:0xf
	s_waitcnt lgkmcnt(0)
	s_nop 1
	v_add_f32_dpp v66, v66, v66 quad_perm:[1,0,3,2] row_mask:0xf bank_mask:0xf
	s_waitcnt lgkmcnt(0)
	s_nop 1
	v_add_f32_dpp v67, v67, v67 quad_perm:[2,3,0,1] row_mask:0xf bank_mask:0xf
	s_waitcnt lgkmcnt(0)
	s_nop 1
	v_add_f32_dpp v66, v66, v66 quad_perm:[2,3,0,1] row_mask:0xf bank_mask:0xf
	s_waitcnt lgkmcnt(0)
	s_nop 1
	v_add_f32_dpp v67, v67, v67 row_half_mirror row_mask:0xf bank_mask:0xf
	s_waitcnt lgkmcnt(0)
	s_nop 1
	v_add_f32_dpp v66, v66, v66 row_half_mirror row_mask:0xf bank_mask:0xf
	s_waitcnt lgkmcnt(0)
	s_nop 1
	v_add_f32_dpp v67, v67, v67 row_mirror row_mask:0xf bank_mask:0xf
	s_waitcnt lgkmcnt(0)
	s_nop 1
	v_add_f32_dpp v66, v66, v66 row_mirror row_mask:0xf bank_mask:0xf
	s_waitcnt lgkmcnt(0)
	s_waitcnt lgkmcnt(0)
	s_waitcnt lgkmcnt(0)
	s_nop 0
	v_readlane_b32 s98, v67, 0
	v_readlane_b32 s99, v67, 16
	v_readlane_b32 s100, v67, 32
	v_readlane_b32 s101, v67, 48
	v_mov_b32_e32 v67, s98
	v_add_f32_e32 v67, s99, v67
	v_mov_b32_e32 v68, s100
	v_add_f32_e32 v68, s101, v68
	v_add_f32_e32 v67, v67, v68
	v_fmamk_f32 v67, v67, 0x3a800000, v231
	v_cmp_gt_f32_e32 vcc, s97, v67
	s_waitcnt lgkmcnt(0)
	s_nop 0
	v_readlane_b32 s98, v66, 0
	v_readlane_b32 s99, v66, 16
	v_readlane_b32 s100, v66, 32
	v_readlane_b32 s101, v66, 48
	v_mov_b32_e32 v66, s98
	v_add_f32_e32 v66, s99, v66
	v_mov_b32_e32 v68, s100
	v_add_f32_e32 v68, s101, v68
	v_add_f32_e32 v66, v66, v68
	v_mul_f32_e32 v68, 0x4f800000, v67
	v_cndmask_b32_e32 v67, v67, v68, vcc
	v_sqrt_f32_e32 v68, v67
	s_nop 0
	v_add_u32_e32 v69, -1, v68
	v_fma_f32 v70, -v69, v68, v67
	v_cmp_ge_f32_e64 s[2:3], 0, v70
	v_add_u32_e32 v70, 1, v68
	s_nop 0
	v_cndmask_b32_e64 v69, v68, v69, s[2:3]
	v_fma_f32 v68, -v70, v68, v67
	v_cmp_lt_f32_e64 s[2:3], 0, v68
	s_nop 1
	v_cndmask_b32_e64 v68, v69, v70, s[2:3]
	v_mul_f32_e32 v69, 0x37800000, v68
	v_cndmask_b32_e32 v68, v68, v69, vcc
	v_cmp_class_f32_e32 vcc, v67, v232
	s_nop 1
	v_cndmask_b32_e32 v67, v68, v67, vcc
	v_div_scale_f32 v68, s[2:3], v67, v67, 1.0
	v_rcp_f32_e32 v69, v68
	s_lshl_b64 s[2:3], s[10:11], 11
	s_add_u32 s2, s4, s2
	s_addc_u32 s3, s5, s3
	v_fma_f32 v70, -v68, v69, 1.0
	v_fmac_f32_e32 v69, v70, v69
	v_div_scale_f32 v70, vcc, 1.0, v67, 1.0
	v_mul_f32_e32 v71, v70, v69
	v_fma_f32 v72, -v68, v71, v70
	v_fmac_f32_e32 v71, v72, v69
	v_fma_f32 v68, -v68, v71, v70
	v_div_fmas_f32 v68, v68, v69, v71
	v_div_fixup_f32 v67, v68, v67, 1.0
	v_mul_f32_e32 v34, v34, v67
	v_fma_f32 v34, v30, v34, v22
	v_mul_f32_e32 v65, v65, v67
	v_mul_f32_e32 v35, v35, v67
	v_mul_f32_e32 v36, v36, v67
	v_mul_f32_e32 v37, v37, v67
	v_fma_f32 v65, v31, v65, v23
	v_fma_f32 v35, v32, v35, v24
	v_mul_f32_e32 v64, v64, v67
	v_fma_f32 v36, v26, v36, v18
	v_mul_f32_e32 v63, v63, v67
	v_fma_f32 v37, v28, v37, v20
	v_mul_f32_e32 v62, v62, v67
	v_cvt_pk_bf16_f32 v34, v34, v65
	v_fma_f32 v64, v33, v64, v25
	v_fma_f32 v63, v27, v63, v19
	v_fma_f32 v62, v29, v62, v21
	v_cvt_pk_bf16_f32 v35, v35, v64
	v_cvt_pk_bf16_f32 v36, v36, v63
	v_cvt_pk_bf16_f32 v37, v37, v62
	global_store_dwordx4 v50, v[34:37], s[2:3]
	s_nop 1
	v_mul_f32_e32 v34, v38, v67
	v_fma_f32 v34, v14, v34, v6
	v_mul_f32_e32 v35, v61, v67
	v_mul_f32_e32 v36, v39, v67
	v_mul_f32_e32 v37, v60, v67
	v_fma_f32 v35, v15, v35, v7
	v_fma_f32 v36, v16, v36, v8
	v_fma_f32 v37, v17, v37, v9
	v_mul_f32_e32 v38, v40, v67
	v_mul_f32_e32 v39, v59, v67
	v_mul_f32_e32 v40, v41, v67
	v_mul_f32_e32 v41, v58, v67
	v_cvt_pk_bf16_f32 v34, v34, v35
	v_fma_f32 v38, v10, v38, v2
	v_fma_f32 v39, v11, v39, v3
	v_fma_f32 v40, v12, v40, v4
	v_fma_f32 v41, v13, v41, v5
	v_cvt_pk_bf16_f32 v35, v36, v37
	v_cvt_pk_bf16_f32 v36, v38, v39
	v_cvt_pk_bf16_f32 v37, v40, v41
	global_store_dwordx4 v50, v[34:37], s[2:3] offset:1024
	s_nop 1
	v_fmamk_f32 v34, v66, 0x3a800000, v231
	v_cmp_gt_f32_e32 vcc, s97, v34
	v_mul_f32_e32 v35, 0x4f800000, v34
	s_nop 0
	v_cndmask_b32_e32 v34, v34, v35, vcc
	v_sqrt_f32_e32 v35, v34
	s_nop 0
	v_add_u32_e32 v36, -1, v35
	v_fma_f32 v37, -v36, v35, v34
	v_cmp_ge_f32_e64 s[2:3], 0, v37
	v_add_u32_e32 v37, 1, v35
	s_nop 0
	v_cndmask_b32_e64 v36, v35, v36, s[2:3]
	v_fma_f32 v35, -v37, v35, v34
	v_cmp_lt_f32_e64 s[2:3], 0, v35
	s_nop 1
	v_cndmask_b32_e64 v35, v36, v37, s[2:3]
	v_mul_f32_e32 v36, 0x37800000, v35
	v_cndmask_b32_e32 v35, v35, v36, vcc
	v_cmp_class_f32_e32 vcc, v34, v232
	s_nop 1
	v_cndmask_b32_e32 v34, v35, v34, vcc
	v_div_scale_f32 v35, s[2:3], v34, v34, 1.0
	v_rcp_f32_e32 v36, v35
	s_or_b32 s2, s8, 31
	s_ashr_i32 s3, s2, 31
	s_lshl_b64 s[2:3], s[2:3], 11
	v_fma_f32 v37, -v35, v36, 1.0
	v_fmac_f32_e32 v36, v37, v36
	v_div_scale_f32 v37, vcc, 1.0, v34, 1.0
	v_mul_f32_e32 v38, v37, v36
	v_fma_f32 v39, -v35, v38, v37
	v_fmac_f32_e32 v38, v39, v36
	v_fma_f32 v35, -v35, v38, v37
	v_div_fmas_f32 v35, v35, v36, v38
	v_div_fixup_f32 v34, v35, v34, 1.0
	v_mul_f32_e32 v35, v42, v34
	v_fma_f32 v22, v30, v35, v22
	v_mul_f32_e32 v30, v57, v34
	v_fma_f32 v23, v31, v30, v23
	v_mul_f32_e32 v30, v43, v34
	v_fma_f32 v24, v32, v30, v24
	v_mul_f32_e32 v30, v56, v34
	v_fmac_f32_e32 v25, v33, v30
	v_mul_f32_e32 v30, v44, v34
	v_fma_f32 v26, v26, v30, v18
	v_mul_f32_e32 v18, v55, v34
	v_fma_f32 v27, v27, v18, v19
	v_mul_f32_e32 v18, v45, v34
	s_add_u32 s2, s4, s2
	v_fma_f32 v28, v28, v18, v20
	v_mul_f32_e32 v18, v54, v34
	s_addc_u32 s3, s5, s3
	v_fmac_f32_e32 v21, v29, v18
	v_cvt_pk_bf16_f32 v18, v22, v23
	v_cvt_pk_bf16_f32 v19, v24, v25
	v_cvt_pk_bf16_f32 v20, v26, v27
	v_cvt_pk_bf16_f32 v21, v28, v21
	global_store_dwordx4 v50, v[18:21], s[2:3]
	v_mul_f32_e32 v0, v0, v34
	v_fmac_f32_e32 v5, v13, v0
	v_mul_f32_e32 v18, v46, v34
	v_fma_f32 v6, v14, v18, v6
	v_mul_f32_e32 v14, v53, v34
	v_fma_f32 v7, v15, v14, v7
	v_mul_f32_e32 v14, v47, v34
	v_fma_f32 v8, v16, v14, v8
	v_mul_f32_e32 v14, v52, v34
	v_fmac_f32_e32 v9, v17, v14
	v_mul_f32_e32 v14, v48, v34
	v_fma_f32 v10, v10, v14, v2
	v_mul_f32_e32 v2, v51, v34
	v_fma_f32 v11, v11, v2, v3
	v_mul_f32_e32 v2, v49, v34
	v_fma_f32 v12, v12, v2, v4
	v_cvt_pk_bf16_f32 v2, v6, v7
	v_cvt_pk_bf16_f32 v3, v8, v9
	v_cvt_pk_bf16_f32 v4, v10, v11
	v_cvt_pk_bf16_f32 v5, v12, v5
	global_store_dwordx4 v50, v[2:5], s[2:3] offset:1024
	v_readlane_b32 s2, v249, 0
	v_readlane_b32 s3, v249, 1
	v_mov_b32_e32 v15, v189
	s_barrier
; #define PG8_STAGE(bufoff, gbase, voff) do { _Pragma("unroll") for (int _i = 0; _i < 2; ++_i) \
;         __builtin_amdgcn_global_load_lds((const unsigned*)((const char*)(gbase) + (voff)[_i]), (LAS unsigned*)(lds + (bufoff) + ldsw + _i * 8192), 16, 0, 0); } while (0)
; #define PG8_WAIT_V(n) asm volatile("s_waitcnt vmcnt(" #n ")" ::: "memory")
; #define PG8_BAR __builtin_amdgcn_s_barrier()
; template <class Epi, class Sched>
; __device__ __forceinline__ void gemm_phase(LAS unsigned char* lds, const Gemm g, const Sched& S, const Epi& E) {
;     ...
;     for (int i = 0; i < 2; ++i) { int R, C; stage_rc(tid * 16 + i * 8192, R, C); const int Rb = Epi::PERM ? ((R & ~31) + perm32(R & 31)) : R;
;         voffA[i] = (unsigned)(R * K + C) * 2u; voffB[i] = (unsigned)(Rb * K + C) * 2u; }
;     const size_t kstep = (size_t)(BK * 2);
;     const size_t hstep = (size_t)HALF * K * 2;
;     const size_t tstep = 2 * hstep;
;     const unsigned ldsw = (unsigned)wid * 1024u;
;     const int aoff = lds_byte(wr * 64 + fr, fq * 8), boff = lds_byte(wc * 32 + fr, fq * 8);
;     ...
;     Unit cur, nxt; int ui = 0;
;     if (!S.next(0, cur)) return;
;     f32x4 acc[2][2][4][2];
; #pragma unroll
;     for (int a = 0; a < 2; ++a)
; #pragma unroll
;         for (int b = 0; b < 2; ++b)
; #pragma unroll
;             for (int m = 0; m < 4; ++m)
; #pragma unroll
;                 for (int n = 0; n < 2; ++n) acc[a][b][m][n] = (f32x4){0.f, 0.f, 0.f, 0.f};
;     bf16x8 At[4][2], B0[2][2], B1[2][2];
;     const char* cA = (const char*)g.A + (size_t)cur.pm * tstep; const char* cB = (const char*)g.Bt + (size_t)cur.pn * tstep;
;     S.a_ready(cur);
;     PG8_STAGE(PG8_SB(0, 0), cB, voffB); PG8_STAGE(PG8_SB(0, 1), cB + hstep, voffB); PG8_STAGE(PG8_SA(0, 0), cA, voffA); PG8_STAGE(PG8_SA(0, 1), cA + hstep, voffA);
;     if (wr == 1) PG8_BAR;
;     PG8_WAIT_V(2); PG8_BAR;
;     PG8_STAGE(PG8_SB(1, 0), cB + kstep, voffB); PG8_STAGE(PG8_SA(1, 0), cA + kstep, voffA); PG8_STAGE(PG8_SB(1, 1), cB + hstep + kstep, voffB);
	s_load_dwordx2 s[46:47], s[2:3], 0xf8
	v_readlane_b32 s2, v249, 8
	v_lshlrev_b32_e32 v0, 4, v15
	v_add_u32_e32 v2, 0x2000, v0
	v_ashrrev_i32_e32 v3, 31, v2
	v_lshrrev_b32_e32 v3, 22, v3
	v_add_u32_e32 v3, v2, v3
	v_ashrrev_i32_e32 v3, 10, v3
	v_mul_i32_i24_e32 v4, 0x400, v3
	v_sub_u32_e32 v2, v2, v4
	v_lshrrev_b32_e32 v4, 4, v2
	v_readlane_b32 s3, v249, 9
	s_waitcnt lgkmcnt(0)
	s_add_u32 s1, s46, s2
	v_bitop3_b32 v2, v4, v2, 32 bitop3:0x6c
	s_addc_u32 s3, s47, s3
	v_readlane_b32 s4, v248, 36
	v_ashrrev_i32_e32 v4, 31, v2
	s_add_u32 s2, s1, 0x6000000
	v_readlane_b32 s5, v248, 37
	v_lshrrev_b32_e32 v4, 26, v4
	s_addc_u32 s3, s3, 0
	s_lshl_b64 s[10:11], s[4:5], 23
	v_add_u32_e32 v4, v2, v4
	v_lshlrev_b32_e32 v6, 3, v3
	s_add_u32 s1, s46, s10
	v_ashrrev_i32_e32 v5, 6, v4
	v_and_b32_e32 v6, -16, v6
	v_lshlrev_b32_e32 v3, 5, v3
	s_addc_u32 s4, s47, s11
	v_add_u32_e32 v6, v5, v6
	v_and_b32_e32 v14, 32, v3
	v_and_b32_e32 v3, 0xc0, v4
	s_add_u32 s18, s1, 0x1000000
	v_and_b32_e32 v5, 3, v5
	s_mov_b32 s1, 0x7fffffe0
	v_lshrrev_b32_e32 v7, 2, v6
	v_lshlrev_b32_e32 v8, 1, v6
	v_sub_u32_e32 v2, v2, v3
	v_and_or_b32 v5, v6, s1, v5
	v_and_b32_e32 v7, 4, v7
	v_and_b32_e32 v8, 24, v8
	v_ashrrev_i16_sdwa v2, v227, sext(v2) dst_sel:DWORD dst_unused:UNUSED_PAD src0_sel:DWORD src1_sel:BYTE_0
	v_or3_b32 v5, v5, v7, v8
	v_bfe_i32 v16, v2, 0, 16
	v_add_u32_e32 v2, v14, v16
	v_mul_lo_u32 v5, v5, s42
	v_mul_lo_u32 v17, v6, s42
	v_add_lshl_u32 v130, v5, v2, 1
	v_add_lshl_u32 v132, v2, v17, 1
	v_bfe_i32 v2, v15, 27, 1
	v_lshrrev_b32_e32 v2, 22, v2
	v_add_u32_e32 v2, v0, v2
	v_and_b32_e32 v2, 0xfffffc00, v2
	v_sub_u32_e32 v0, v0, v2
	v_lshrrev_b32_e32 v2, 4, v0
	v_ashrrev_i32_e32 v4, 31, v15
	v_bitop3_b32 v0, v2, v0, 32 bitop3:0x6c
	v_lshrrev_b32_e32 v4, 26, v4
	v_ashrrev_i32_e32 v2, 31, v0
	v_add_u32_e32 v4, v15, v4
	v_lshrrev_b32_e32 v2, 26, v2
	v_ashrrev_i32_e32 v4, 6, v4
	v_add_u32_e32 v2, v0, v2
	v_lshlrev_b32_e32 v5, 3, v4
	v_ashrrev_i32_e32 v3, 6, v2
	v_and_b32_e32 v5, -16, v5
	v_add_u32_e32 v5, v3, v5
	v_and_b32_e32 v2, 0xc0, v2
	v_readfirstlane_b32 s8, v15
	v_and_b32_e32 v3, 3, v3
	v_lshrrev_b32_e32 v6, 2, v5
	v_lshlrev_b32_e32 v7, 1, v5
	v_sub_u32_e32 v0, v0, v2
	s_addc_u32 s19, s4, 0
	s_ashr_i32 s9, s8, 6
	v_and_or_b32 v3, v5, s1, v3
	v_and_b32_e32 v6, 4, v6
	v_and_b32_e32 v7, 24, v7
	v_lshlrev_b32_e32 v4, 5, v4
	v_ashrrev_i16_sdwa v0, v227, sext(v0) dst_sel:DWORD dst_unused:UNUSED_PAD src0_sel:DWORD src1_sel:BYTE_0
	s_lshl_b32 s4, s9, 10
	v_or3_b32 v3, v3, v6, v7
	v_and_b32_e32 v18, 32, v4
	v_bfe_i32 v19, v0, 0, 16
	v_mul_lo_u32 v3, v3, s42
	v_add_u32_e32 v2, v18, v19
	s_add_i32 s5, s4, 0
	s_ashr_i32 s43, s42, 31
	v_add_lshl_u32 v0, v3, v2, 1
	s_add_i32 m0, s5, 0x10000
	s_ashr_i32 s36, s8, 8
	s_lshl_b64 s[26:27], s[42:43], 8
	global_load_lds_dwordx4 v0, s[18:19]
	s_add_i32 m0, s5, 0x12000
	s_add_u32 s38, s18, s26
	global_load_lds_dwordx4 v130, s[18:19]
	s_addc_u32 s39, s19, s27
	s_add_i32 m0, s5, 0x14000
	v_mul_lo_u32 v20, v5, s42
	global_load_lds_dwordx4 v0, s[38:39]
	s_add_i32 m0, s5, 0x16000
	s_add_i32 s54, s5, 0x2000
	v_add_lshl_u32 v134, v2, v20, 1
	v_lshl_add_u64 v[6:7], s[38:39], 0, v[0:1]
	v_lshl_add_u64 v[8:9], s[38:39], 0, v[130:131]
	global_load_lds_dwordx4 v130, s[38:39]
	s_mov_b32 m0, s5
	s_add_u32 s38, s2, s26
	global_load_lds_dwordx4 v134, s[2:3]
	s_mov_b32 m0, s54
	s_addc_u32 s39, s3, s27
	s_add_i32 s55, s5, 0x4000
	global_load_lds_dwordx4 v132, s[2:3]
	s_mov_b32 m0, s55
	s_add_i32 s56, s5, 0x6000
	global_load_lds_dwordx4 v134, s[38:39]
	s_mov_b32 m0, s56
	s_cmp_eq_u32 s36, 1
	global_load_lds_dwordx4 v132, s[38:39]
	v_lshl_add_u64 v[2:3], s[18:19], 0, v[0:1]
	v_lshl_add_u64 v[4:5], s[18:19], 0, v[130:131]
	v_lshl_add_u64 v[10:11], s[2:3], 0, v[134:135]
	v_lshl_add_u64 v[12:13], s[2:3], 0, v[132:133]
	s_cselect_b64 s[38:39], -1, 0
	s_cmp_lg_u32 s36, 1
	s_cbranch_scc1 .LBB0_428
	s_barrier

; __device__ __forceinline__ float bflo(unsigned w) { return __uint_as_float(w << 16); }
; __device__ __forceinline__ float bfhi(unsigned w) { return __uint_as_float(w & 0xffff0000u); }
; __device__ __forceinline__ void ln_panel_b(bf16_t* hb, float* outf, const float* gam, const float* bet) {
;     ...
;     for (int it = 0; it < 32 / NB; ++it) {
;         const int r = r0 + it * NB;
;         float v[NB][16];
; #pragma unroll
;         for (int b = 0; b < NB; ++b)
; #pragma unroll
;             for (int j = 0; j < 2; ++j)
; #pragma unroll
;                 for (int k = 0; k < 4; ++k) { v[b][8 * j + 2 * k] = bflo(nxt[b][j][k]); v[b][8 * j + 2 * k + 1] = bfhi(nxt[b][j][k]); }
;         if (it + 1 < 32 / NB) {
; #pragma unroll
;             for (int b = 0; b < NB; ++b)
; #pragma unroll
;                 for (int j = 0; j < 2; ++j) nxt[b][j] = ((const u32x4*)(hb + (size_t)(r + NB + b) * DM))[lane + 64 * j];
;         }
;         float s[NB], s2[NB];
; #pragma unroll
;         for (int b = 0; b < NB; ++b) { s[b] = 0.f;
; #pragma unroll
;             for (int k = 0; k < 16; ++k) s[b] += v[b][k]; }
; #pragma unroll
;         for (int o = 1; o < 64; o <<= 1)
; #pragma unroll
;             for (int b = 0; b < NB; ++b) s[b] += __shfl_xor(s[b], o);
; #pragma unroll
;         for (int b = 0; b < NB; ++b) { const float mean = s[b] * (1.f / DM); s2[b] = 0.f;
; #pragma unroll
;             for (int k = 0; k < 16; ++k) { v[b][k] -= mean; s2[b] += v[b][k] * v[b][k]; } }
; #pragma unroll
;         for (int o = 1; o < 64; o <<= 1)
; #pragma unroll
;             for (int b = 0; b < NB; ++b) s2[b] += __shfl_xor(s2[b], o);
.LBB0_458:
	s_waitcnt vmcnt(0)
	v_lshlrev_b32_e32 v76, 16, v54
	v_and_b32_e32 v77, 0xffff0000, v54
	v_add_f32_e32 v0, 0, v76
	v_add_f32_e32 v0, v0, v77
	v_lshlrev_b32_e32 v54, 16, v55
	v_and_b32_e32 v55, 0xffff0000, v55
	v_add_f32_e32 v0, v0, v54
	v_lshlrev_b32_e32 v86, 16, v64
	v_and_b32_e32 v87, 0xffff0000, v64
	v_lshlrev_b32_e32 v84, 16, v65
	v_and_b32_e32 v85, 0xffff0000, v65
	v_lshlrev_b32_e32 v90, 16, v62
	v_and_b32_e32 v91, 0xffff0000, v62
	v_lshlrev_b32_e32 v88, 16, v63
	v_and_b32_e32 v89, 0xffff0000, v63
	v_lshlrev_b32_e32 v62, 16, v60
	v_and_b32_e32 v63, 0xffff0000, v60
	v_lshlrev_b32_e32 v64, 16, v61
	v_and_b32_e32 v65, 0xffff0000, v61
	v_lshlrev_b32_e32 v60, 16, v58
	v_and_b32_e32 v61, 0xffff0000, v58
	v_lshlrev_b32_e32 v58, 16, v56
	v_add_f32_e32 v0, v0, v55
	v_lshlrev_b32_e32 v92, 16, v59
	v_and_b32_e32 v93, 0xffff0000, v59
	v_and_b32_e32 v59, 0xffff0000, v56
	v_add_f32_e32 v0, v0, v58
	v_lshlrev_b32_e32 v56, 16, v57
	v_add_f32_e32 v0, v0, v59
	v_and_b32_e32 v57, 0xffff0000, v57
	v_add_f32_e32 v0, v0, v56
	v_add_f32_e32 v0, v0, v57
	v_add_f32_e32 v0, v0, v60
	v_add_f32_e32 v0, v0, v61
	v_add_f32_e32 v0, v0, v92
	v_add_f32_e32 v0, v0, v93
	v_add_f32_e32 v0, v0, v62
	v_add_f32_e32 v0, v0, v63
	v_add_f32_e32 v0, v0, v64
	v_add_f32_e32 v0, v0, v65
	v_lshl_add_u64 v[74:75], v[70:71], 0, s[20:21]
	v_add_co_u32_e32 v42, vcc, 0x6001000, v74
	s_waitcnt lgkmcnt(0)
	s_nop 1
	v_add_f32_dpp v0, v0, v0 quad_perm:[1,0,3,2] row_mask:0xf bank_mask:0xf
	v_addc_co_u32_e32 v43, vcc, 0, v75, vcc
	global_load_dwordx4 v[34:37], v[42:43], off
	global_load_dwordx4 v[46:49], v[42:43], off offset:1024
	global_load_dwordx4 v[38:41], v[42:43], off offset:2048
	s_nop 0
	global_load_dwordx4 v[42:45], v[42:43], off offset:3072
	s_waitcnt lgkmcnt(0)
	s_nop 1
	v_add_f32_dpp v0, v0, v0 quad_perm:[2,3,0,1] row_mask:0xf bank_mask:0xf
	s_waitcnt lgkmcnt(0)
	s_nop 1
	v_add_f32_dpp v0, v0, v0 row_half_mirror row_mask:0xf bank_mask:0xf
	s_waitcnt lgkmcnt(0)
	s_nop 1
	v_add_f32_dpp v0, v0, v0 row_mirror row_mask:0xf bank_mask:0xf
	s_waitcnt lgkmcnt(0)
	s_waitcnt lgkmcnt(0)
	s_nop 0
	v_readlane_b32 s98, v0, 0
	v_readlane_b32 s99, v0, 16
	v_readlane_b32 s100, v0, 32
	v_readlane_b32 s101, v0, 48
	v_mov_b32_e32 v0, s98
	v_add_f32_e32 v0, s99, v0
	v_mov_b32_e32 v67, s100
	v_add_f32_e32 v67, s101, v67
	v_add_f32_e32 v0, v0, v67
	v_mul_f32_e32 v0, 0x3a800000, v0
	v_pk_add_f32 v[76:77], v[76:77], v[0:1] op_sel_hi:[1,0] neg_lo:[0,1] neg_hi:[0,1]
	v_pk_add_f32 v[78:79], v[54:55], v[0:1] op_sel_hi:[1,0] neg_lo:[0,1] neg_hi:[0,1]
	v_pk_mul_f32 v[94:95], v[76:77], v[76:77]
	v_pk_mul_f32 v[54:55], v[78:79], v[78:79]
	v_pk_add_f32 v[80:81], v[58:59], v[0:1] op_sel_hi:[1,0] neg_lo:[0,1] neg_hi:[0,1]
	v_pk_add_f32 v[82:83], v[56:57], v[0:1] op_sel_hi:[1,0] neg_lo:[0,1] neg_hi:[0,1]
	v_pk_add_f32 v[58:59], v[60:61], v[0:1] op_sel_hi:[1,0] neg_lo:[0,1] neg_hi:[0,1]
	v_pk_add_f32 v[60:61], v[92:93], v[0:1] op_sel_hi:[1,0] neg_lo:[0,1] neg_hi:[0,1]
	v_pk_add_f32 v[62:63], v[62:63], v[0:1] op_sel_hi:[1,0] neg_lo:[0,1] neg_hi:[0,1]
	v_pk_add_f32 v[64:65], v[64:65], v[0:1] op_sel_hi:[1,0] neg_lo:[0,1] neg_hi:[0,1]
	v_add_f32_e32 v0, v94, v95
	v_add_f32_e32 v0, v54, v0
	v_pk_mul_f32 v[96:97], v[80:81], v[80:81]
	v_add_f32_e32 v0, v55, v0
	v_add_f32_e32 v0, v96, v0
	v_pk_mul_f32 v[56:57], v[82:83], v[82:83]
	v_add_f32_e32 v0, v97, v0
	v_add_f32_e32 v0, v56, v0
	v_pk_mul_f32 v[98:99], v[58:59], v[58:59]
	v_add_f32_e32 v0, v57, v0
	v_add_f32_e32 v0, v98, v0
	v_pk_mul_f32 v[92:93], v[60:61], v[60:61]
	v_add_f32_e32 v0, v99, v0
	v_add_f32_e32 v0, v92, v0
	v_pk_mul_f32 v[100:101], v[62:63], v[62:63]
	v_add_f32_e32 v0, v93, v0
	v_add_f32_e32 v0, v100, v0
	v_pk_mul_f32 v[102:103], v[64:65], v[64:65]
	v_add_f32_e32 v0, v101, v0
	v_add_f32_e32 v0, v102, v0
	v_add_f32_e32 v0, v103, v0
	v_lshlrev_b32_e32 v56, 16, v50
	v_and_b32_e32 v57, 0xffff0000, v50
	v_add_f32_e32 v50, 0, v56
	v_add_f32_e32 v69, v50, v57
	s_waitcnt lgkmcnt(0)
	s_nop 1
	v_add_f32_dpp v0, v0, v0 quad_perm:[1,0,3,2] row_mask:0xf bank_mask:0xf
	v_lshlrev_b32_e32 v50, 16, v51
	v_and_b32_e32 v51, 0xffff0000, v51
	v_add_f32_e32 v69, v69, v50
	v_add_f32_e32 v69, v69, v51
	s_waitcnt lgkmcnt(0)
	s_nop 1
	v_add_f32_dpp v0, v0, v0 quad_perm:[2,3,0,1] row_mask:0xf bank_mask:0xf
	v_and_b32_e32 v55, 0xffff0000, v52
	s_waitcnt lgkmcnt(0)
	s_nop 1
	v_add_f32_dpp v0, v0, v0 row_half_mirror row_mask:0xf bank_mask:0xf
	s_waitcnt lgkmcnt(0)
	s_nop 1
	v_add_f32_dpp v0, v0, v0 row_mirror row_mask:0xf bank_mask:0xf
	s_waitcnt lgkmcnt(0)
	v_lshlrev_b32_e32 v54, 16, v52
	v_add_f32_e32 v69, v69, v54
	v_lshlrev_b32_e32 v52, 16, v53
	v_add_f32_e32 v69, v69, v55
	v_and_b32_e32 v53, 0xffff0000, v53
	v_add_f32_e32 v69, v69, v52
	v_add_f32_e32 v69, v69, v53
	v_add_f32_e32 v69, v69, v90
	v_add_f32_e32 v69, v69, v91
	v_add_f32_e32 v69, v69, v88
	v_add_f32_e32 v69, v69, v89
	v_add_f32_e32 v69, v69, v86
	v_add_f32_e32 v69, v69, v87
	v_add_f32_e32 v69, v69, v84
	v_add_f32_e32 v69, v69, v85
	s_waitcnt lgkmcnt(1)
; __device__ __forceinline__ unsigned pk2(float lo, float hi) { unsigned r; asm("v_cvt_pk_bf16_f32 %0, %1, %2" : "=v"(r) : "v"(lo), "v"(hi)); return r; }
; __device__ __forceinline__ void ln_panel_b(bf16_t* hb, float* outf, const float* gam, const float* bet) {
;     ...
;         for (int b = 0; b < NB; ++b) { const float mean = s[b] * (1.f / DM); s2[b] = 0.f;
; #pragma unroll
;             for (int k = 0; k < 16; ++k) { v[b][k] -= mean; s2[b] += v[b][k] * v[b][k]; } }
; #pragma unroll
;         for (int o = 1; o < 64; o <<= 1)
; #pragma unroll
;             for (int b = 0; b < NB; ++b) s2[b] += __shfl_xor(s2[b], o);
; #pragma unroll
;         for (int b = 0; b < NB; ++b) {
;             const float rstd = 1.f / sqrtf(s2[b] * (1.f / DM) + LN_EPS);
; #pragma unroll
;             for (int j = 0; j < 2; ++j) {
;                 float o[8];
; #pragma unroll
;                 for (int k = 0; k < 8; ++k) o[k] = v[b][8 * j + k] * rstd * gv[j][k >> 2][k & 3] + bv[j][k >> 2][k & 3];
;                 if (outf) { f32x4* op = (f32x4*)(outf + (size_t)(r + b) * DM + 512 * j + 8 * lane); op[0] = (f32x4){o[0], o[1], o[2], o[3]}; op[1] = (f32x4){o[4], o[5], o[6], o[7]}; }
;                 else { u32x4 w; w.x = pk2(o[0], o[1]); w.y = pk2(o[2], o[3]); w.z = pk2(o[4], o[5]); w.w = pk2(o[6], o[7]); ((u32x4*)(hb + (size_t)(r + b) * DM))[lane + 64 * j] = w; }
	s_nop 1
	v_add_f32_dpp v69, v69, v69 quad_perm:[1,0,3,2] row_mask:0xf bank_mask:0xf
	s_waitcnt lgkmcnt(0)
	s_nop 1
	v_add_f32_dpp v69, v69, v69 quad_perm:[2,3,0,1] row_mask:0xf bank_mask:0xf
	s_waitcnt lgkmcnt(0)
	s_nop 1
	v_add_f32_dpp v69, v69, v69 row_half_mirror row_mask:0xf bank_mask:0xf
	s_waitcnt lgkmcnt(0)
	s_nop 1
	v_add_f32_dpp v69, v69, v69 row_mirror row_mask:0xf bank_mask:0xf
	s_waitcnt lgkmcnt(0)
	s_waitcnt lgkmcnt(0)
	s_nop 0
	v_readlane_b32 s98, v69, 0
	v_readlane_b32 s99, v69, 16
	v_readlane_b32 s100, v69, 32
	v_readlane_b32 s101, v69, 48
	v_mov_b32_e32 v69, s98
	v_add_f32_e32 v69, s99, v69
	v_mov_b32_e32 v92, s100
	v_add_f32_e32 v92, s101, v92
	v_add_f32_e32 v69, v69, v92
	v_mul_f32_e32 v92, 0x3a800000, v69
	v_pk_add_f32 v[56:57], v[56:57], v[92:93] op_sel_hi:[1,0] neg_lo:[0,1] neg_hi:[0,1]
	v_pk_add_f32 v[50:51], v[50:51], v[92:93] op_sel_hi:[1,0] neg_lo:[0,1] neg_hi:[0,1]
	v_pk_mul_f32 v[94:95], v[56:57], v[56:57]
	v_pk_mul_f32 v[96:97], v[50:51], v[50:51]
	v_add_f32_e32 v69, v94, v95
	v_pk_add_f32 v[98:99], v[54:55], v[92:93] op_sel_hi:[1,0] neg_lo:[0,1] neg_hi:[0,1]
	v_add_f32_e32 v69, v96, v69
	v_pk_mul_f32 v[54:55], v[98:99], v[98:99]
	v_add_f32_e32 v69, v97, v69
	v_pk_add_f32 v[52:53], v[52:53], v[92:93] op_sel_hi:[1,0] neg_lo:[0,1] neg_hi:[0,1]
	v_add_f32_e32 v54, v54, v69
	v_pk_mul_f32 v[100:101], v[52:53], v[52:53]
	v_add_f32_e32 v54, v55, v54
	v_pk_add_f32 v[90:91], v[90:91], v[92:93] op_sel_hi:[1,0] neg_lo:[0,1] neg_hi:[0,1]
	v_add_f32_e32 v54, v100, v54
	v_pk_mul_f32 v[102:103], v[90:91], v[90:91]
	v_add_f32_e32 v54, v101, v54
	v_pk_add_f32 v[88:89], v[88:89], v[92:93] op_sel_hi:[1,0] neg_lo:[0,1] neg_hi:[0,1]
	v_add_f32_e32 v54, v102, v54
	v_pk_mul_f32 v[104:105], v[88:89], v[88:89]
	v_add_f32_e32 v54, v103, v54
	v_pk_add_f32 v[86:87], v[86:87], v[92:93] op_sel_hi:[1,0] neg_lo:[0,1] neg_hi:[0,1]
	v_add_f32_e32 v54, v104, v54
	v_pk_mul_f32 v[106:107], v[86:87], v[86:87]
	v_add_f32_e32 v54, v105, v54
	v_pk_add_f32 v[84:85], v[84:85], v[92:93] op_sel_hi:[1,0] neg_lo:[0,1] neg_hi:[0,1]
	v_add_f32_e32 v54, v106, v54
	v_pk_mul_f32 v[92:93], v[84:85], v[84:85]
	v_add_f32_e32 v54, v107, v54
	v_add_f32_e32 v54, v92, v54
	v_add_f32_e32 v54, v93, v54
	s_waitcnt lgkmcnt(0)
	s_nop 1
	v_add_f32_dpp v54, v54, v54 quad_perm:[1,0,3,2] row_mask:0xf bank_mask:0xf
	s_waitcnt lgkmcnt(0)
	s_nop 1
	v_add_f32_dpp v54, v54, v54 quad_perm:[2,3,0,1] row_mask:0xf bank_mask:0xf
	s_waitcnt lgkmcnt(0)
	s_nop 1
	v_add_f32_dpp v54, v54, v54 row_half_mirror row_mask:0xf bank_mask:0xf
	s_waitcnt lgkmcnt(0)
	s_nop 1
	v_add_f32_dpp v54, v54, v54 row_mirror row_mask:0xf bank_mask:0xf
	s_waitcnt lgkmcnt(0)
	s_waitcnt lgkmcnt(0)
	s_nop 0
	v_readlane_b32 s98, v54, 0
	v_readlane_b32 s99, v54, 16
	v_readlane_b32 s100, v54, 32
	v_readlane_b32 s101, v54, 48
	v_mov_b32_e32 v54, s98
	v_add_f32_e32 v54, s99, v54
	v_mov_b32_e32 v55, s100
	v_add_f32_e32 v55, s101, v55
	v_add_f32_e32 v54, v54, v55
	v_fmamk_f32 v54, v54, 0x3a800000, v231
	v_cmp_gt_f32_e32 vcc, s97, v54
	v_mul_f32_e32 v55, 0x4f800000, v54
	s_nop 0
	v_cndmask_b32_e32 v54, v54, v55, vcc
	v_sqrt_f32_e32 v55, v54
	s_nop 0
	v_add_u32_e32 v69, -1, v55
	v_fma_f32 v92, -v69, v55, v54
	v_cmp_ge_f32_e64 s[2:3], 0, v92
	v_add_u32_e32 v92, 1, v55
	s_nop 0
	v_cndmask_b32_e64 v69, v55, v69, s[2:3]
	v_fma_f32 v55, -v92, v55, v54
	v_cmp_lt_f32_e64 s[2:3], 0, v55
	s_nop 1
	v_cndmask_b32_e64 v55, v69, v92, s[2:3]
	v_mul_f32_e32 v69, 0x37800000, v55
	v_cndmask_b32_e32 v55, v55, v69, vcc
	v_cmp_class_f32_e32 vcc, v54, v232
	s_nop 1
	v_cndmask_b32_e32 v54, v55, v54, vcc
	v_div_scale_f32 v55, s[2:3], v54, v54, 1.0
	v_rcp_f32_e32 v69, v55
	s_nop 0
	v_fma_f32 v92, -v55, v69, 1.0
	v_fmac_f32_e32 v69, v92, v69
	v_div_scale_f32 v92, vcc, 1.0, v54, 1.0
	v_mul_f32_e32 v93, v92, v69
	v_fma_f32 v94, -v55, v93, v92
	v_fmac_f32_e32 v93, v94, v69
	v_fma_f32 v55, -v55, v93, v92
	v_div_fmas_f32 v55, v55, v69, v93
	v_div_fixup_f32 v92, v55, v54, 1.0
	v_pk_mul_f32 v[50:51], v[50:51], v[92:93] op_sel_hi:[1,0]
	v_pk_mul_f32 v[54:55], v[56:57], v[92:93] op_sel_hi:[1,0]
	v_pk_fma_f32 v[56:57], v[28:29], v[50:51], v[32:33]
	v_pk_mul_f32 v[50:51], v[98:99], v[92:93] op_sel_hi:[1,0]
	v_pk_mul_f32 v[52:53], v[52:53], v[92:93] op_sel_hi:[1,0]
	v_cndmask_b32_e64 v69, 0, 1, s[26:27]
	v_pk_fma_f32 v[54:55], v[26:27], v[54:55], v[30:31]
	v_pk_fma_f32 v[50:51], v[18:19], v[50:51], v[22:23]
	v_pk_fma_f32 v[52:53], v[20:21], v[52:53], v[24:25]
	v_cmp_ne_u32_e64 s[2:3], 1, v69
	s_andn2_b64 vcc, exec, s[26:27]
	s_cbranch_vccnz .LBB0_469
	global_store_dwordx4 v[72:73], v[54:57], off offset:-4096
	global_store_dwordx4 v[72:73], v[50:53], off offset:-4080
	s_cbranch_execnz .LBB0_461

; __device__ __forceinline__ unsigned pk2(float lo, float hi) { unsigned r; asm("v_cvt_pk_bf16_f32 %0, %1, %2" : "=v"(r) : "v"(lo), "v"(hi)); return r; }
; __device__ __forceinline__ void ln_panel_b(bf16_t* hb, float* outf, const float* gam, const float* bet) {
;     ...
;         for (int b = 0; b < NB; ++b) {
;             const float rstd = 1.f / sqrtf(s2[b] * (1.f / DM) + LN_EPS);
; #pragma unroll
;             for (int j = 0; j < 2; ++j) {
;                 float o[8];
; #pragma unroll
;                 for (int k = 0; k < 8; ++k) o[k] = v[b][8 * j + k] * rstd * gv[j][k >> 2][k & 3] + bv[j][k >> 2][k & 3];
;                 if (outf) { f32x4* op = (f32x4*)(outf + (size_t)(r + b) * DM + 512 * j + 8 * lane); op[0] = (f32x4){o[0], o[1], o[2], o[3]}; op[1] = (f32x4){o[4], o[5], o[6], o[7]}; }
;                 else { u32x4 w; w.x = pk2(o[0], o[1]); w.y = pk2(o[2], o[3]); w.z = pk2(o[4], o[5]); w.w = pk2(o[6], o[7]); ((u32x4*)(hb + (size_t)(r + b) * DM))[lane + 64 * j] = w; }
.LBB0_464:
	s_nop 0
	v_readlane_b32 s98, v0, 0
	v_readlane_b32 s99, v0, 16
	v_readlane_b32 s100, v0, 32
	v_readlane_b32 s101, v0, 48
	v_mov_b32_e32 v0, s98
	v_add_f32_e32 v0, s99, v0
	v_mov_b32_e32 v67, s100
	v_add_f32_e32 v67, s101, v67
	v_add_f32_e32 v0, v0, v67
	v_fmamk_f32 v0, v0, 0x3a800000, v231
	v_mul_f32_e32 v50, 0x4f800000, v0
	v_cmp_gt_f32_e32 vcc, s97, v0
	s_nop 1
	v_cndmask_b32_e32 v0, v0, v50, vcc
	v_sqrt_f32_e32 v50, v0
	s_nop 0
	v_add_u32_e32 v51, -1, v50
	v_fma_f32 v53, -v51, v50, v0
	v_add_u32_e32 v52, 1, v50
	v_cmp_ge_f32_e64 s[40:41], 0, v53
	s_nop 1
	v_cndmask_b32_e64 v51, v50, v51, s[40:41]
	v_fma_f32 v50, -v52, v50, v0
	v_cmp_lt_f32_e64 s[40:41], 0, v50
	s_nop 1
	v_cndmask_b32_e64 v50, v51, v52, s[40:41]
	v_mul_f32_e32 v51, 0x37800000, v50
	v_cndmask_b32_e32 v50, v50, v51, vcc
	v_cmp_class_f32_e32 vcc, v0, v232
	s_nop 1
	v_cndmask_b32_e32 v0, v50, v0, vcc
	v_div_scale_f32 v50, s[8:9], v0, v0, 1.0
	v_rcp_f32_e32 v51, v50
	s_nop 0
	v_fma_f32 v52, -v50, v51, 1.0
	v_fmac_f32_e32 v51, v52, v51
	v_div_scale_f32 v52, vcc, 1.0, v0, 1.0
	v_mul_f32_e32 v53, v52, v51
	v_fma_f32 v54, -v50, v53, v52
	v_fmac_f32_e32 v53, v54, v51
	v_fma_f32 v50, -v50, v53, v52
	v_div_fmas_f32 v50, v50, v51, v53
	v_div_fixup_f32 v84, v50, v0, 1.0
	v_pk_mul_f32 v[50:51], v[76:77], v[84:85] op_sel_hi:[1,0]
	v_pk_mul_f32 v[52:53], v[82:83], v[84:85] op_sel_hi:[1,0]
	v_pk_fma_f32 v[54:55], v[26:27], v[50:51], v[30:31]
	v_pk_mul_f32 v[50:51], v[78:79], v[84:85] op_sel_hi:[1,0]
	s_and_b64 vcc, exec, s[2:3]
	v_pk_fma_f32 v[56:57], v[28:29], v[50:51], v[32:33]
	v_pk_mul_f32 v[50:51], v[80:81], v[84:85] op_sel_hi:[1,0]
	v_pk_fma_f32 v[52:53], v[20:21], v[52:53], v[24:25]
	v_pk_fma_f32 v[50:51], v[18:19], v[50:51], v[22:23]
	s_cbranch_vccnz .LBB0_471
	global_store_dwordx4 v[72:73], v[54:57], off
	global_store_dwordx4 v[72:73], v[50:53], off offset:16
	s_cbranch_execnz .LBB0_467

; __device__ __forceinline__ float bflo(unsigned w) { return __uint_as_float(w << 16); }
; __device__ __forceinline__ float bfhi(unsigned w) { return __uint_as_float(w & 0xffff0000u); }
; __device__ __forceinline__ void ln_panel_b(bf16_t* hb, float* outf, const float* gam, const float* bet) {
;     ...
; #pragma unroll
;         for (int b = 0; b < NB; ++b)
; #pragma unroll
;             for (int j = 0; j < 2; ++j)
; #pragma unroll
;                 for (int k = 0; k < 4; ++k) { v[b][8 * j + 2 * k] = bflo(nxt[b][j][k]); v[b][8 * j + 2 * k + 1] = bfhi(nxt[b][j][k]); }
;         if (it + 1 < 32 / NB) {
; #pragma unroll
;             for (int b = 0; b < NB; ++b)
; #pragma unroll
;                 for (int j = 0; j < 2; ++j) nxt[b][j] = ((const u32x4*)(hb + (size_t)(r + NB + b) * DM))[lane + 64 * j];
;         }
;         float s[NB], s2[NB];
; #pragma unroll
;         for (int b = 0; b < NB; ++b) { s[b] = 0.f;
; #pragma unroll
;             for (int k = 0; k < 16; ++k) s[b] += v[b][k]; }
; #pragma unroll
;         for (int o = 1; o < 64; o <<= 1)
; #pragma unroll
;             for (int b = 0; b < NB; ++b) s[b] += __shfl_xor(s[b], o);
; #pragma unroll
;         for (int b = 0; b < NB; ++b) { const float mean = s[b] * (1.f / DM); s2[b] = 0.f;
; #pragma unroll
;             for (int k = 0; k < 16; ++k) { v[b][k] -= mean; s2[b] += v[b][k] * v[b][k]; } }
; #pragma unroll
;         for (int o = 1; o < 64; o <<= 1)
; #pragma unroll
;             for (int b = 0; b < NB; ++b) s2[b] += __shfl_xor(s2[b], o);
.LBB0_474:
	v_lshlrev_b32_e32 v0, 2, v68
	v_lshlrev_b32_e32 v52, 16, v38
	v_lshl_add_u64 v[50:51], s[10:11], 0, v[0:1]
	v_and_b32_e32 v53, 0xffff0000, v38
	v_add_f32_e32 v0, 0, v52
	v_add_f32_e32 v0, v0, v53
	v_lshlrev_b32_e32 v38, 16, v39
	v_and_b32_e32 v39, 0xffff0000, v39
	v_add_f32_e32 v0, v0, v38
	v_lshlrev_b32_e32 v64, 16, v48
	v_and_b32_e32 v65, 0xffff0000, v48
	v_lshlrev_b32_e32 v62, 16, v49
	v_and_b32_e32 v63, 0xffff0000, v49
	v_lshlrev_b32_e32 v70, 16, v46
	v_and_b32_e32 v71, 0xffff0000, v46
	v_lshlrev_b32_e32 v68, 16, v47
	v_and_b32_e32 v69, 0xffff0000, v47
	v_lshlrev_b32_e32 v46, 16, v44
	v_and_b32_e32 v47, 0xffff0000, v44
	v_lshlrev_b32_e32 v48, 16, v45
	v_and_b32_e32 v49, 0xffff0000, v45
	v_lshlrev_b32_e32 v44, 16, v42
	v_and_b32_e32 v45, 0xffff0000, v42
	v_lshlrev_b32_e32 v42, 16, v40
	v_add_f32_e32 v0, v0, v39
	v_lshlrev_b32_e32 v60, 16, v43
	v_and_b32_e32 v61, 0xffff0000, v43
	v_and_b32_e32 v43, 0xffff0000, v40
	v_add_f32_e32 v0, v0, v42
	v_lshlrev_b32_e32 v40, 16, v41
	v_add_f32_e32 v0, v0, v43
	v_and_b32_e32 v41, 0xffff0000, v41
	v_add_f32_e32 v0, v0, v40
	v_add_f32_e32 v0, v0, v41
	v_add_f32_e32 v0, v0, v44
	v_add_f32_e32 v0, v0, v45
	v_add_f32_e32 v0, v0, v60
	v_add_f32_e32 v0, v0, v61
	v_add_f32_e32 v0, v0, v46
	v_add_f32_e32 v0, v0, v47
	v_add_f32_e32 v0, v0, v48
	v_add_f32_e32 v0, v0, v49
	s_or_b32 s10, s18, 30
	s_ashr_i32 s11, s10, 31
	s_lshl_b64 s[8:9], s[10:11], 12
	s_waitcnt lgkmcnt(0)
	s_nop 1
	v_add_f32_dpp v0, v0, v0 quad_perm:[1,0,3,2] row_mask:0xf bank_mask:0xf
	s_waitcnt lgkmcnt(0)
	s_nop 1
	v_add_f32_dpp v0, v0, v0 quad_perm:[2,3,0,1] row_mask:0xf bank_mask:0xf
	s_waitcnt lgkmcnt(0)
	s_nop 1
	v_add_f32_dpp v0, v0, v0 row_half_mirror row_mask:0xf bank_mask:0xf
	s_waitcnt lgkmcnt(0)
	s_nop 1
	v_add_f32_dpp v0, v0, v0 row_mirror row_mask:0xf bank_mask:0xf
	s_waitcnt lgkmcnt(0)
	s_waitcnt lgkmcnt(0)
	s_nop 0
	v_readlane_b32 s98, v0, 0
	v_readlane_b32 s99, v0, 16
	v_readlane_b32 s100, v0, 32
	v_readlane_b32 s101, v0, 48
	v_mov_b32_e32 v0, s98
	v_add_f32_e32 v0, s99, v0
	v_mov_b32_e32 v54, s100
	v_add_f32_e32 v54, s101, v54
	v_add_f32_e32 v0, v0, v54
	v_mul_f32_e32 v0, 0x3a800000, v0
	v_pk_add_f32 v[52:53], v[52:53], v[0:1] op_sel_hi:[1,0] neg_lo:[0,1] neg_hi:[0,1]
	v_pk_add_f32 v[54:55], v[38:39], v[0:1] op_sel_hi:[1,0] neg_lo:[0,1] neg_hi:[0,1]
	v_pk_mul_f32 v[72:73], v[52:53], v[52:53]
	v_pk_mul_f32 v[38:39], v[54:55], v[54:55]
	v_pk_add_f32 v[56:57], v[42:43], v[0:1] op_sel_hi:[1,0] neg_lo:[0,1] neg_hi:[0,1]
	v_pk_add_f32 v[58:59], v[40:41], v[0:1] op_sel_hi:[1,0] neg_lo:[0,1] neg_hi:[0,1]
	v_pk_add_f32 v[42:43], v[44:45], v[0:1] op_sel_hi:[1,0] neg_lo:[0,1] neg_hi:[0,1]
	v_pk_add_f32 v[44:45], v[60:61], v[0:1] op_sel_hi:[1,0] neg_lo:[0,1] neg_hi:[0,1]
	v_pk_add_f32 v[46:47], v[46:47], v[0:1] op_sel_hi:[1,0] neg_lo:[0,1] neg_hi:[0,1]
	v_pk_add_f32 v[48:49], v[48:49], v[0:1] op_sel_hi:[1,0] neg_lo:[0,1] neg_hi:[0,1]
	v_add_f32_e32 v0, v72, v73
	v_add_f32_e32 v0, v38, v0
	v_pk_mul_f32 v[74:75], v[56:57], v[56:57]
	v_add_f32_e32 v0, v39, v0
	v_add_f32_e32 v0, v74, v0
	v_pk_mul_f32 v[40:41], v[58:59], v[58:59]
	v_add_f32_e32 v0, v75, v0
	v_add_f32_e32 v0, v40, v0
	v_pk_mul_f32 v[76:77], v[42:43], v[42:43]
	v_add_f32_e32 v0, v41, v0
	v_add_f32_e32 v0, v76, v0
	v_pk_mul_f32 v[60:61], v[44:45], v[44:45]
	v_add_f32_e32 v0, v77, v0
	v_add_f32_e32 v0, v60, v0
	v_pk_mul_f32 v[78:79], v[46:47], v[46:47]
	v_add_f32_e32 v0, v61, v0
	v_add_f32_e32 v0, v78, v0
	v_pk_mul_f32 v[80:81], v[48:49], v[48:49]
	v_add_f32_e32 v0, v79, v0
	v_add_f32_e32 v0, v80, v0
	v_add_f32_e32 v0, v81, v0
	v_lshlrev_b32_e32 v40, 16, v34
	v_and_b32_e32 v41, 0xffff0000, v34
	v_add_f32_e32 v34, 0, v40
	v_add_f32_e32 v72, v34, v41
	s_waitcnt lgkmcnt(0)
	s_nop 1
	v_add_f32_dpp v0, v0, v0 quad_perm:[1,0,3,2] row_mask:0xf bank_mask:0xf
	v_lshlrev_b32_e32 v34, 16, v35
	v_and_b32_e32 v35, 0xffff0000, v35
	v_add_f32_e32 v72, v72, v34
	v_add_f32_e32 v72, v72, v35
	s_waitcnt lgkmcnt(0)
	s_nop 1
	v_add_f32_dpp v0, v0, v0 quad_perm:[2,3,0,1] row_mask:0xf bank_mask:0xf
	v_and_b32_e32 v39, 0xffff0000, v36
	v_lshl_add_u64 v[60:61], v[50:51], 0, s[8:9]
	s_lshl_b64 s[8:9], s[10:11], 11
	s_add_u32 s10, s4, s8
	s_waitcnt lgkmcnt(0)
	s_nop 1
	v_add_f32_dpp v0, v0, v0 row_half_mirror row_mask:0xf bank_mask:0xf
	s_addc_u32 s11, s5, s9
	s_waitcnt lgkmcnt(0)
	s_nop 1
	v_add_f32_dpp v0, v0, v0 row_mirror row_mask:0xf bank_mask:0xf
	s_waitcnt lgkmcnt(0)
	v_lshlrev_b32_e32 v38, 16, v36
	v_add_f32_e32 v72, v72, v38
	v_lshlrev_b32_e32 v36, 16, v37
	v_add_f32_e32 v72, v72, v39
	v_and_b32_e32 v37, 0xffff0000, v37
	v_add_f32_e32 v72, v72, v36
	v_add_f32_e32 v72, v72, v37
	v_add_f32_e32 v72, v72, v70
	v_add_f32_e32 v72, v72, v71
	v_add_f32_e32 v72, v72, v68
	v_add_f32_e32 v72, v72, v69
	v_add_f32_e32 v72, v72, v64
	v_add_f32_e32 v72, v72, v65
	v_add_f32_e32 v72, v72, v62
	v_add_f32_e32 v72, v72, v63
	s_waitcnt lgkmcnt(1)
; __device__ __forceinline__ unsigned pk2(float lo, float hi) { unsigned r; asm("v_cvt_pk_bf16_f32 %0, %1, %2" : "=v"(r) : "v"(lo), "v"(hi)); return r; }
; __device__ __forceinline__ void ln_panel_b(bf16_t* hb, float* outf, const float* gam, const float* bet) {
;     ...
;         for (int b = 0; b < NB; ++b) { const float mean = s[b] * (1.f / DM); s2[b] = 0.f;
; #pragma unroll
;             for (int k = 0; k < 16; ++k) { v[b][k] -= mean; s2[b] += v[b][k] * v[b][k]; } }
; #pragma unroll
;         for (int o = 1; o < 64; o <<= 1)
; #pragma unroll
;             for (int b = 0; b < NB; ++b) s2[b] += __shfl_xor(s2[b], o);
; #pragma unroll
;         for (int b = 0; b < NB; ++b) {
;             const float rstd = 1.f / sqrtf(s2[b] * (1.f / DM) + LN_EPS);
; #pragma unroll
;             for (int j = 0; j < 2; ++j) {
;                 float o[8];
; #pragma unroll
;                 for (int k = 0; k < 8; ++k) o[k] = v[b][8 * j + k] * rstd * gv[j][k >> 2][k & 3] + bv[j][k >> 2][k & 3];
;                 if (outf) { f32x4* op = (f32x4*)(outf + (size_t)(r + b) * DM + 512 * j + 8 * lane); op[0] = (f32x4){o[0], o[1], o[2], o[3]}; op[1] = (f32x4){o[4], o[5], o[6], o[7]}; }
;                 else { u32x4 w; w.x = pk2(o[0], o[1]); w.y = pk2(o[2], o[3]); w.z = pk2(o[4], o[5]); w.w = pk2(o[6], o[7]); ((u32x4*)(hb + (size_t)(r + b) * DM))[lane + 64 * j] = w; }
	s_nop 1
	v_add_f32_dpp v72, v72, v72 quad_perm:[1,0,3,2] row_mask:0xf bank_mask:0xf
	s_waitcnt lgkmcnt(0)
	s_nop 1
	v_add_f32_dpp v72, v72, v72 quad_perm:[2,3,0,1] row_mask:0xf bank_mask:0xf
	s_waitcnt lgkmcnt(0)
	s_nop 1
	v_add_f32_dpp v72, v72, v72 row_half_mirror row_mask:0xf bank_mask:0xf
	s_waitcnt lgkmcnt(0)
	s_nop 1
	v_add_f32_dpp v72, v72, v72 row_mirror row_mask:0xf bank_mask:0xf
	s_waitcnt lgkmcnt(0)
	s_waitcnt lgkmcnt(0)
	s_nop 0
	v_readlane_b32 s98, v72, 0
	v_readlane_b32 s99, v72, 16
	v_readlane_b32 s100, v72, 32
	v_readlane_b32 s101, v72, 48
	v_mov_b32_e32 v72, s98
	v_add_f32_e32 v72, s99, v72
	v_mov_b32_e32 v73, s100
	v_add_f32_e32 v73, s101, v73
	v_add_f32_e32 v72, v72, v73
	v_mul_f32_e32 v72, 0x3a800000, v72
	v_pk_add_f32 v[40:41], v[40:41], v[72:73] op_sel_hi:[1,0] neg_lo:[0,1] neg_hi:[0,1]
	v_pk_add_f32 v[34:35], v[34:35], v[72:73] op_sel_hi:[1,0] neg_lo:[0,1] neg_hi:[0,1]
	v_pk_mul_f32 v[74:75], v[40:41], v[40:41]
	v_pk_mul_f32 v[76:77], v[34:35], v[34:35]
	v_add_f32_e32 v74, v74, v75
	v_pk_add_f32 v[78:79], v[38:39], v[72:73] op_sel_hi:[1,0] neg_lo:[0,1] neg_hi:[0,1]
	v_add_f32_e32 v74, v76, v74
	v_pk_mul_f32 v[38:39], v[78:79], v[78:79]
	v_add_f32_e32 v74, v77, v74
	v_pk_add_f32 v[36:37], v[36:37], v[72:73] op_sel_hi:[1,0] neg_lo:[0,1] neg_hi:[0,1]
	v_add_f32_e32 v38, v38, v74
	v_pk_mul_f32 v[80:81], v[36:37], v[36:37]
	v_add_f32_e32 v38, v39, v38
	v_pk_add_f32 v[70:71], v[70:71], v[72:73] op_sel_hi:[1,0] neg_lo:[0,1] neg_hi:[0,1]
	v_add_f32_e32 v38, v80, v38
	v_pk_mul_f32 v[82:83], v[70:71], v[70:71]
	v_add_f32_e32 v38, v81, v38
	v_pk_add_f32 v[68:69], v[68:69], v[72:73] op_sel_hi:[1,0] neg_lo:[0,1] neg_hi:[0,1]
	v_add_f32_e32 v38, v82, v38
	v_pk_mul_f32 v[84:85], v[68:69], v[68:69]
	v_add_f32_e32 v38, v83, v38
	v_pk_add_f32 v[64:65], v[64:65], v[72:73] op_sel_hi:[1,0] neg_lo:[0,1] neg_hi:[0,1]
	v_add_f32_e32 v38, v84, v38
	v_pk_mul_f32 v[86:87], v[64:65], v[64:65]
	v_add_f32_e32 v38, v85, v38
	v_pk_add_f32 v[62:63], v[62:63], v[72:73] op_sel_hi:[1,0] neg_lo:[0,1] neg_hi:[0,1]
	v_add_f32_e32 v38, v86, v38
	v_pk_mul_f32 v[72:73], v[62:63], v[62:63]
	v_add_f32_e32 v38, v87, v38
	v_add_f32_e32 v38, v72, v38
	v_add_f32_e32 v38, v73, v38
	s_waitcnt lgkmcnt(0)
	s_nop 1
	v_add_f32_dpp v38, v38, v38 quad_perm:[1,0,3,2] row_mask:0xf bank_mask:0xf
	s_waitcnt lgkmcnt(0)
	s_nop 1
	v_add_f32_dpp v38, v38, v38 quad_perm:[2,3,0,1] row_mask:0xf bank_mask:0xf
	s_waitcnt lgkmcnt(0)
	s_nop 1
	v_add_f32_dpp v38, v38, v38 row_half_mirror row_mask:0xf bank_mask:0xf
	s_waitcnt lgkmcnt(0)
	s_nop 1
	v_add_f32_dpp v38, v38, v38 row_mirror row_mask:0xf bank_mask:0xf
	s_waitcnt lgkmcnt(0)
	s_waitcnt lgkmcnt(0)
	s_nop 0
	v_readlane_b32 s98, v38, 0
	v_readlane_b32 s99, v38, 16
	v_readlane_b32 s100, v38, 32
	v_readlane_b32 s101, v38, 48
	v_mov_b32_e32 v38, s98
	v_add_f32_e32 v38, s99, v38
	v_mov_b32_e32 v39, s100
	v_add_f32_e32 v39, s101, v39
	v_add_f32_e32 v38, v38, v39
	v_fmamk_f32 v38, v38, 0x3a800000, v231
	v_cmp_gt_f32_e32 vcc, s97, v38
	v_mul_f32_e32 v39, 0x4f800000, v38
	s_nop 0
	v_cndmask_b32_e32 v38, v38, v39, vcc
	v_sqrt_f32_e32 v39, v38
	s_nop 0
	v_add_u32_e32 v72, -1, v39
	v_fma_f32 v73, -v72, v39, v38
	v_cmp_ge_f32_e64 s[40:41], 0, v73
	v_add_u32_e32 v73, 1, v39
	s_nop 0
	v_cndmask_b32_e64 v72, v39, v72, s[40:41]
	v_fma_f32 v39, -v73, v39, v38
	v_cmp_lt_f32_e64 s[40:41], 0, v39
	s_nop 1
	v_cndmask_b32_e64 v39, v72, v73, s[40:41]
	v_mul_f32_e32 v72, 0x37800000, v39
	v_cndmask_b32_e32 v39, v39, v72, vcc
	v_cmp_class_f32_e32 vcc, v38, v232
	s_nop 1
	v_cndmask_b32_e32 v38, v39, v38, vcc
	v_div_scale_f32 v39, s[8:9], v38, v38, 1.0
	v_rcp_f32_e32 v72, v39
	s_nop 0
	v_fma_f32 v73, -v39, v72, 1.0
	v_fmac_f32_e32 v72, v73, v72
	v_div_scale_f32 v73, vcc, 1.0, v38, 1.0
	v_mul_f32_e32 v74, v73, v72
	v_fma_f32 v75, -v39, v74, v73
	v_fmac_f32_e32 v74, v75, v72
	v_fma_f32 v39, -v39, v74, v73
	v_div_fmas_f32 v39, v39, v72, v74
	v_div_fixup_f32 v72, v39, v38, 1.0
	v_pk_mul_f32 v[34:35], v[34:35], v[72:73] op_sel_hi:[1,0]
	v_pk_mul_f32 v[38:39], v[40:41], v[72:73] op_sel_hi:[1,0]
	v_pk_fma_f32 v[40:41], v[28:29], v[34:35], v[32:33]
	v_pk_mul_f32 v[34:35], v[78:79], v[72:73] op_sel_hi:[1,0]
	v_pk_mul_f32 v[36:37], v[36:37], v[72:73] op_sel_hi:[1,0]
	v_pk_fma_f32 v[38:39], v[26:27], v[38:39], v[30:31]
	v_pk_fma_f32 v[34:35], v[18:19], v[34:35], v[22:23]
	v_pk_fma_f32 v[36:37], v[20:21], v[36:37], v[24:25]
	s_and_b64 vcc, exec, s[2:3]
	s_cbranch_vccnz .LBB0_485
	global_store_dwordx4 v[60:61], v[38:41], off
	global_store_dwordx4 v[60:61], v[34:37], off offset:16
	v_lshlrev_b32_e32 v66, 4, v66
	s_cbranch_execnz .LBB0_477

; __device__ __forceinline__ unsigned pk2(float lo, float hi) { unsigned r; asm("v_cvt_pk_bf16_f32 %0, %1, %2" : "=v"(r) : "v"(lo), "v"(hi)); return r; }
; __device__ __forceinline__ void ln_panel_b(bf16_t* hb, float* outf, const float* gam, const float* bet) {
;     ...
;         for (int b = 0; b < NB; ++b) {
;             const float rstd = 1.f / sqrtf(s2[b] * (1.f / DM) + LN_EPS);
; #pragma unroll
;             for (int j = 0; j < 2; ++j) {
;                 float o[8];
; #pragma unroll
;                 for (int k = 0; k < 8; ++k) o[k] = v[b][8 * j + k] * rstd * gv[j][k >> 2][k & 3] + bv[j][k >> 2][k & 3];
;                 if (outf) { f32x4* op = (f32x4*)(outf + (size_t)(r + b) * DM + 512 * j + 8 * lane); op[0] = (f32x4){o[0], o[1], o[2], o[3]}; op[1] = (f32x4){o[4], o[5], o[6], o[7]}; }
;                 else { u32x4 w; w.x = pk2(o[0], o[1]); w.y = pk2(o[2], o[3]); w.z = pk2(o[4], o[5]); w.w = pk2(o[6], o[7]); ((u32x4*)(hb + (size_t)(r + b) * DM))[lane + 64 * j] = w; }
.LBB0_480:
	s_nop 0
	v_readlane_b32 s98, v0, 0
	v_readlane_b32 s99, v0, 16
	v_readlane_b32 s100, v0, 32
	v_readlane_b32 s101, v0, 48
	v_mov_b32_e32 v0, s98
	v_add_f32_e32 v0, s99, v0
	v_mov_b32_e32 v67, s100
	v_add_f32_e32 v67, s101, v67
	v_add_f32_e32 v0, v0, v67
	v_fmamk_f32 v0, v0, 0x3a800000, v231
	v_mul_f32_e32 v34, 0x4f800000, v0
	v_cmp_gt_f32_e32 vcc, s97, v0
	s_nop 1
	v_cndmask_b32_e32 v0, v0, v34, vcc
	v_sqrt_f32_e32 v34, v0
	s_nop 0
	v_add_u32_e32 v35, -1, v34
	v_fma_f32 v37, -v35, v34, v0
	v_add_u32_e32 v36, 1, v34
	v_cmp_ge_f32_e64 s[40:41], 0, v37
	s_nop 1
	v_cndmask_b32_e64 v35, v34, v35, s[40:41]
	v_fma_f32 v34, -v36, v34, v0
	v_cmp_lt_f32_e64 s[40:41], 0, v34
	s_nop 1
	v_cndmask_b32_e64 v34, v35, v36, s[40:41]
	v_mul_f32_e32 v35, 0x37800000, v34
	v_cndmask_b32_e32 v34, v34, v35, vcc
	v_cmp_class_f32_e32 vcc, v0, v232
	s_nop 1
	v_cndmask_b32_e32 v0, v34, v0, vcc
	v_div_scale_f32 v34, s[8:9], v0, v0, 1.0
	v_rcp_f32_e32 v35, v34
	s_or_b32 s8, s36, 31
	s_ashr_i32 s9, s8, 31
	s_lshl_b64 s[10:11], s[8:9], 12
	v_fma_f32 v36, -v34, v35, 1.0
	v_fmac_f32_e32 v35, v36, v35
	v_div_scale_f32 v36, vcc, 1.0, v0, 1.0
	v_mul_f32_e32 v37, v36, v35
	v_fma_f32 v38, -v34, v37, v36
	v_fmac_f32_e32 v37, v38, v35
	v_fma_f32 v34, -v34, v37, v36
	v_div_fmas_f32 v34, v34, v35, v37
	v_div_fixup_f32 v36, v34, v0, 1.0
	v_pk_mul_f32 v[38:39], v[52:53], v[36:37] op_sel_hi:[1,0]
	s_lshl_b64 s[8:9], s[8:9], 11
	v_pk_fma_f32 v[26:27], v[26:27], v[38:39], v[30:31]
	v_pk_mul_f32 v[30:31], v[54:55], v[36:37] op_sel_hi:[1,0]
	v_lshl_add_u64 v[34:35], v[50:51], 0, s[10:11]
	v_pk_fma_f32 v[28:29], v[28:29], v[30:31], v[32:33]
	v_pk_mul_f32 v[30:31], v[56:57], v[36:37] op_sel_hi:[1,0]
	s_add_u32 s10, s4, s8
	v_pk_fma_f32 v[18:19], v[18:19], v[30:31], v[22:23]
	v_pk_mul_f32 v[22:23], v[58:59], v[36:37] op_sel_hi:[1,0]
	s_addc_u32 s11, s5, s9
	s_and_b64 vcc, exec, s[2:3]
	v_pk_fma_f32 v[20:21], v[20:21], v[22:23], v[24:25]
	s_cbranch_vccnz .LBB0_487
	global_store_dwordx4 v[34:35], v[26:29], off
	global_store_dwordx4 v[34:35], v[18:21], off offset:16
	s_cbranch_execnz .LBB0_483

; __global__ void __launch_bounds__(512, 2) fwd_megakernel(Args a) {
	.amdhsa_kernel _Z14fwd_megakernel4Args
		.amdhsa_group_segment_fixed_size 0
		.amdhsa_private_segment_fixed_size 0
		.amdhsa_kernarg_size 512
		.amdhsa_user_sgpr_count 2
		.amdhsa_user_sgpr_dispatch_ptr 0
		.amdhsa_user_sgpr_queue_ptr 0
		.amdhsa_user_sgpr_kernarg_segment_ptr 1
		.amdhsa_user_sgpr_dispatch_id 0
		.amdhsa_user_sgpr_kernarg_preload_length 0
		.amdhsa_user_sgpr_kernarg_preload_offset 0
		.amdhsa_user_sgpr_private_segment_size 0
		.amdhsa_uses_dynamic_stack 0
		.amdhsa_enable_private_segment 0
		.amdhsa_system_sgpr_workgroup_id_x 1
		.amdhsa_system_sgpr_workgroup_id_y 0
		.amdhsa_system_sgpr_workgroup_id_z 0
		.amdhsa_system_sgpr_workgroup_info 0
		.amdhsa_system_vgpr_workitem_id 2
		.amdhsa_next_free_vgpr 250
		.amdhsa_next_free_sgpr 102
		.amdhsa_accum_offset 252
		.amdhsa_reserve_vcc 1
		.amdhsa_float_round_mode_32 0
		.amdhsa_float_round_mode_16_64 0
		.amdhsa_float_denorm_mode_32 3
		.amdhsa_float_denorm_mode_16_64 3
		.amdhsa_dx10_clamp 1
		.amdhsa_ieee_mode 1
		.amdhsa_fp16_overflow 0
		.amdhsa_tg_split 0
		.amdhsa_exception_fp_ieee_invalid_op 0
		.amdhsa_exception_fp_denorm_src 0
		.amdhsa_exception_fp_ieee_div_zero 0
		.amdhsa_exception_fp_ieee_overflow 0
		.amdhsa_exception_fp_ieee_underflow 0
		.amdhsa_exception_fp_ieee_inexact 0
		.amdhsa_exception_int_div_zero 0
	.end_amdhsa_kernel

; __global__ void __launch_bounds__(512, 2) fwd_megakernel(Args a) {
amdhsa.kernels:
  - .agpr_count:     0
    .args:
      - .offset:         0
        .size:           256
        .value_kind:     by_value
      - .offset:         256
        .size:           4
        .value_kind:     hidden_block_count_x
      - .offset:         260
        .size:           4
        .value_kind:     hidden_block_count_y
      - .offset:         264
        .size:           4
        .value_kind:     hidden_block_count_z
      - .offset:         268
        .size:           2
        .value_kind:     hidden_group_size_x
      - .offset:         270
        .size:           2
        .value_kind:     hidden_group_size_y
      - .offset:         272
        .size:           2
        .value_kind:     hidden_group_size_z
      - .offset:         274
        .size:           2
        .value_kind:     hidden_remainder_x
      - .offset:         276
        .size:           2
        .value_kind:     hidden_remainder_y
      - .offset:         278
        .size:           2
        .value_kind:     hidden_remainder_z
      - .offset:         296
        .size:           8
        .value_kind:     hidden_global_offset_x
      - .offset:         304
        .size:           8
        .value_kind:     hidden_global_offset_y
      - .offset:         312
        .size:           8
        .value_kind:     hidden_global_offset_z
      - .offset:         320
        .size:           2
        .value_kind:     hidden_grid_dims
      - .offset:         344
        .size:           8
        .value_kind:     hidden_multigrid_sync_arg
      - .offset:         376
        .size:           4
        .value_kind:     hidden_dynamic_lds_size
    .group_segment_fixed_size: 0
    .kernarg_segment_align: 8
    .kernarg_segment_size: 512
    .language:       OpenCL C
    .language_version:
      - 2
      - 0
    .max_flat_workgroup_size: 512
    .name:           _Z14fwd_megakernel4Args
    .private_segment_fixed_size: 0
    .sgpr_count:     108
    .sgpr_spill_count: 104
    .symbol:         _Z14fwd_megakernel4Args.kd
    .uniform_work_group_size: 1
    .uses_dynamic_stack: false
    .vgpr_count:     250
    .vgpr_spill_count: 0
    .wavefront_size: 64
